# v27 + removed the mid-block s_setprio 0 / s_setprio 1 pair in the 16 MFMA blocks
# speedup vs baseline: 1.0061x; 1.0020x over previous
; #define PG8_STAGE(bufoff, gbase, voff) do { _Pragma("unroll") for (int _i = 0; _i < 2; ++_i) \
;         __builtin_amdgcn_global_load_lds((const unsigned*)((const char*)(gbase) + (voff)[_i]), (PG8_LAS unsigned*)(lds + (bufoff) + ldsw + _i * 8192), 16, 0, 0); } while (0)
; #define PG8_LDA(dst, b, h) do { _Pragma("unroll") for (int m = 0; m < 4; ++m) _Pragma("unroll") for (int k = 0; k < 2; ++k) dst[m][k] = *(const PG8_LAS bf16x8*)(lds + PG8_SA(b, h) + aoff + m * 2048 + k * 1024); } while (0)
; #define PG8_LDB(dst, b, h) do { _Pragma("unroll") for (int n = 0; n < 2; ++n) _Pragma("unroll") for (int k = 0; k < 2; ++k) dst[n][k] = *(const PG8_LAS bf16x8*)(lds + PG8_SB(b, h) + boff + n * 2048 + k * 1024); } while (0)
; #define PG8_MMA(ai, bj, At, Bt) do { __builtin_amdgcn_s_setprio(1); _Pragma("unroll") for (int m = 0; m < 4; ++m) _Pragma("unroll") for (int n = 0; n < 2; ++n) _Pragma("unroll") for (int k = 0; k < 2; ++k) \
;         acc[ai][bj][m][n] = __builtin_amdgcn_mfma_f32_16x16x32_bf16(Bt[n][k], At[m][k], acc[ai][bj][m][n], 0, 0, 0); __builtin_amdgcn_s_setprio(0); } while (0)
; #define PG8_WAIT_V(n) asm volatile("s_waitcnt vmcnt(" #n ")" ::: "memory")
; #define PG8_WAIT_L(n) asm volatile("s_waitcnt lgkmcnt(" #n ")" ::: "memory")
; #define PG8_BAR __builtin_amdgcn_s_barrier()
; #define PG8_SCHED __builtin_amdgcn_sched_barrier(0)
; template <class Epi, class Sched, bool ALIGN_EPI = false, bool SP2 = false>
; __device__ __forceinline__ void gemm_phase(PG8_LAS unsigned char* lds, const Gemm g, const Sched& S, const Epi& E, int tid_in) {
;     ...
;             PG8_LDB(B0, 0, 0); PG8_LDB(B1, 0, 1); PG8_SCHED; PG8_LDA(At, 0, 0); PG8_STAGE(PG8_SA(1, 1), a1 + hstep, voffA);
;             PG8_WAIT_V(8); PG8_WAIT_L(0); PG8_BAR; PG8_MMA(0, 0, At, B0); PG8_MMA(0, 1, At, B1); PG8_BAR; PG8_SCHED;
;             PG8_LDA(At, 0, 1); PG8_STAGE(PG8_SB(0, 0), b2, voffB); PG8_STAGE(PG8_SB(0, 1), b2 + hstep, voffB); PG8_STAGE(PG8_SA(0, 0), a2, voffA);
;             PG8_WAIT_V(8); PG8_WAIT_L(0); PG8_BAR; PG8_MMA(1, 0, At, B0); PG8_MMA(1, 1, At, B1); PG8_BAR; PG8_SCHED;
.LBB0_158:
	v_or_b32_e32 v32, 0x10000, v194
	v_add_u32_e32 v36, 0x10400, v194
	v_add_u32_e32 v44, 0x10800, v194
	v_add_u32_e32 v48, 0x10c00, v194
	v_or_b32_e32 v81, 0x14000, v194
	v_add_u32_e32 v162, 0x14400, v194
	ds_read_b128 v[32:35], v32
	ds_read_b128 v[36:39], v36
	ds_read_b128 v[44:47], v44
	ds_read_b128 v[48:51], v48
	ds_read_b128 v[158:161], v81
	ds_read_b128 v[162:165], v162
	v_add_u32_e32 v81, 0x14800, v194
	v_add_u32_e32 v170, 0x14c00, v194
	ds_read_b128 v[166:169], v81
	ds_read_b128 v[170:173], v170
	s_add_u32 s29, s84, 0xfffc0080
	s_addc_u32 s31, s85, -1
	s_cmp_eq_u32 s27, 12
	s_cselect_b32 s89, s21, s31
	s_cselect_b32 s88, s22, s29
	s_cselect_b32 s87, s23, s26
	s_cselect_b32 s86, s24, s25
	s_mov_b32 m0, s63
	v_lshl_add_u64 v[174:175], s[84:85], 0, v[154:155]
	ds_read_b128 v[182:185], v177
	ds_read_b128 v[200:203], v177 offset:1024
	ds_read_b128 v[204:207], v177 offset:2048
	ds_read_b128 v[208:211], v177 offset:3072
	ds_read_b128 v[212:215], v177 offset:4096
	ds_read_b128 v[216:219], v177 offset:5120
	ds_read_b128 v[226:229], v177 offset:6144
	ds_read_b128 v[232:235], v177 offset:7168
	global_load_lds_dwordx4 v[174:175], off
	v_lshl_add_u64 v[174:175], s[84:85], 0, v[156:157]
	s_mov_b32 m0, s62
	s_nop 0
	global_load_lds_dwordx4 v[174:175], off
	s_waitcnt vmcnt(8)
	s_waitcnt lgkmcnt(0)
	s_barrier
	s_setprio 1
	s_waitcnt lgkmcnt(0)
	v_mfma_f32_16x16x32_bf16 v[142:145], v[32:35], v[182:185], v[142:145]
	v_mfma_f32_16x16x32_bf16 v[138:141], v[44:47], v[182:185], v[138:141]
	v_mfma_f32_16x16x32_bf16 v[126:129], v[32:35], v[204:207], v[126:129]
	v_mfma_f32_16x16x32_bf16 v[122:125], v[44:47], v[204:207], v[122:125]
	v_mfma_f32_16x16x32_bf16 v[110:113], v[32:35], v[212:215], v[110:113]
	v_mfma_f32_16x16x32_bf16 v[106:109], v[44:47], v[212:215], v[106:109]
	v_mfma_f32_16x16x32_bf16 v[94:97], v[32:35], v[226:229], v[94:97]
	v_mfma_f32_16x16x32_bf16 v[90:93], v[44:47], v[226:229], v[90:93]
	v_mfma_f32_16x16x32_bf16 v[142:145], v[36:39], v[200:203], v[142:145]
	v_mfma_f32_16x16x32_bf16 v[138:141], v[48:51], v[200:203], v[138:141]
	v_mfma_f32_16x16x32_bf16 v[126:129], v[36:39], v[208:211], v[126:129]
	v_mfma_f32_16x16x32_bf16 v[122:125], v[48:51], v[208:211], v[122:125]
	v_mfma_f32_16x16x32_bf16 v[110:113], v[36:39], v[216:219], v[110:113]
	v_mfma_f32_16x16x32_bf16 v[106:109], v[48:51], v[216:219], v[106:109]
	v_mfma_f32_16x16x32_bf16 v[94:97], v[36:39], v[232:235], v[94:97]
	v_mfma_f32_16x16x32_bf16 v[90:93], v[48:51], v[232:235], v[90:93]
	v_mfma_f32_16x16x32_bf16 v[134:137], v[158:161], v[182:185], v[134:137]
	v_mfma_f32_16x16x32_bf16 v[130:133], v[166:169], v[182:185], v[130:133]
	v_mfma_f32_16x16x32_bf16 v[118:121], v[158:161], v[204:207], v[118:121]
	v_mfma_f32_16x16x32_bf16 v[114:117], v[166:169], v[204:207], v[114:117]
	v_mfma_f32_16x16x32_bf16 v[102:105], v[158:161], v[212:215], v[102:105]
	v_mfma_f32_16x16x32_bf16 v[98:101], v[166:169], v[212:215], v[98:101]
	v_mfma_f32_16x16x32_bf16 v[86:89], v[158:161], v[226:229], v[86:89]
	v_mfma_f32_16x16x32_bf16 v[82:85], v[166:169], v[226:229], v[82:85]
	v_mfma_f32_16x16x32_bf16 v[134:137], v[162:165], v[200:203], v[134:137]
	v_mfma_f32_16x16x32_bf16 v[130:133], v[170:173], v[200:203], v[130:133]
	v_mfma_f32_16x16x32_bf16 v[118:121], v[162:165], v[208:211], v[118:121]
	v_mfma_f32_16x16x32_bf16 v[114:117], v[170:173], v[208:211], v[114:117]
	v_mfma_f32_16x16x32_bf16 v[102:105], v[162:165], v[216:219], v[102:105]
	v_mfma_f32_16x16x32_bf16 v[98:101], v[170:173], v[216:219], v[98:101]
	v_mfma_f32_16x16x32_bf16 v[86:89], v[162:165], v[232:235], v[86:89]
	s_barrier
	v_mfma_f32_16x16x32_bf16 v[82:85], v[170:173], v[232:235], v[82:85]
	s_setprio 0
	s_mov_b32 m0, s43
	v_lshl_add_u64 v[174:175], s[86:87], 0, v[148:149]
	s_add_u32 s58, s86, 0x40000
	ds_read_b128 v[182:185], v177 offset:16384
	ds_read_b128 v[200:203], v177 offset:17408
	ds_read_b128 v[204:207], v177 offset:18432
	ds_read_b128 v[208:211], v177 offset:19456
	ds_read_b128 v[212:215], v177 offset:20480
	ds_read_b128 v[216:219], v177 offset:21504
	ds_read_b128 v[226:229], v177 offset:22528
	ds_read_b128 v[232:235], v177 offset:23552
	global_load_lds_dwordx4 v[174:175], off
	v_lshl_add_u64 v[178:179], s[86:87], 0, v[152:153]
	s_mov_b32 m0, s92
	s_addc_u32 s59, s87, 0
	global_load_lds_dwordx4 v[178:179], off
	v_lshl_add_u64 v[180:181], s[58:59], 0, v[148:149]
	s_mov_b32 m0, s93
	v_lshl_add_u64 v[236:237], s[88:89], 0, v[150:151]
	global_load_lds_dwordx4 v[180:181], off
	v_lshl_add_u64 v[180:181], s[58:59], 0, v[152:153]
	s_mov_b32 m0, s94
	s_nop 0
	global_load_lds_dwordx4 v[180:181], off
	v_lshl_add_u64 v[180:181], s[88:89], 0, v[146:147]
	s_mov_b32 m0, s70
	s_nop 0
	global_load_lds_dwordx4 v[180:181], off
	s_mov_b32 m0, s95
	s_nop 0
	global_load_lds_dwordx4 v[236:237], off
	s_waitcnt vmcnt(8)
	s_waitcnt lgkmcnt(0)
	s_barrier
; #define PG8_STAGE(bufoff, gbase, voff) do { _Pragma("unroll") for (int _i = 0; _i < 2; ++_i) \
;         __builtin_amdgcn_global_load_lds((const unsigned*)((const char*)(gbase) + (voff)[_i]), (PG8_LAS unsigned*)(lds + (bufoff) + ldsw + _i * 8192), 16, 0, 0); } while (0)
; #define PG8_LDA(dst, b, h) do { _Pragma("unroll") for (int m = 0; m < 4; ++m) _Pragma("unroll") for (int k = 0; k < 2; ++k) dst[m][k] = *(const PG8_LAS bf16x8*)(lds + PG8_SA(b, h) + aoff + m * 2048 + k * 1024); } while (0)
; #define PG8_LDB(dst, b, h) do { _Pragma("unroll") for (int n = 0; n < 2; ++n) _Pragma("unroll") for (int k = 0; k < 2; ++k) dst[n][k] = *(const PG8_LAS bf16x8*)(lds + PG8_SB(b, h) + boff + n * 2048 + k * 1024); } while (0)
; #define PG8_MMA(ai, bj, At, Bt) do { __builtin_amdgcn_s_setprio(1); _Pragma("unroll") for (int m = 0; m < 4; ++m) _Pragma("unroll") for (int n = 0; n < 2; ++n) _Pragma("unroll") for (int k = 0; k < 2; ++k) \
;         acc[ai][bj][m][n] = __builtin_amdgcn_mfma_f32_16x16x32_bf16(Bt[n][k], At[m][k], acc[ai][bj][m][n], 0, 0, 0); __builtin_amdgcn_s_setprio(0); } while (0)
; #define PG8_WAIT_V(n) asm volatile("s_waitcnt vmcnt(" #n ")" ::: "memory")
; #define PG8_WAIT_L(n) asm volatile("s_waitcnt lgkmcnt(" #n ")" ::: "memory")
; #define PG8_BAR __builtin_amdgcn_s_barrier()
; #define PG8_SCHED __builtin_amdgcn_sched_barrier(0)
; template <class Epi, class Sched, bool ALIGN_EPI = false, bool SP2 = false>
; __device__ __forceinline__ void gemm_phase(PG8_LAS unsigned char* lds, const Gemm g, const Sched& S, const Epi& E, int tid_in) {
;     ...
;             PG8_WAIT_V(8); PG8_WAIT_L(0); PG8_BAR; PG8_MMA(1, 0, At, B0); PG8_MMA(1, 1, At, B1); PG8_BAR; PG8_SCHED;
;             PG8_LDB(B0, 1, 0); PG8_LDB(B1, 1, 1); PG8_SCHED; PG8_LDA(At, 1, 0); PG8_STAGE(PG8_SA(0, 1), a2 + hstep, voffA);
;             PG8_WAIT_V(8); PG8_WAIT_L(0); PG8_BAR; PG8_MMA(0, 0, At, B0); PG8_MMA(0, 1, At, B1); PG8_BAR; PG8_SCHED;
	s_setprio 1
	s_waitcnt lgkmcnt(0)
	v_mfma_f32_16x16x32_bf16 v[76:79], v[32:35], v[182:185], v[76:79]
	v_mfma_f32_16x16x32_bf16 v[72:75], v[44:47], v[182:185], v[72:75]
	v_mfma_f32_16x16x32_bf16 v[60:63], v[32:35], v[204:207], v[60:63]
	v_mfma_f32_16x16x32_bf16 v[56:59], v[44:47], v[204:207], v[56:59]
	v_mfma_f32_16x16x32_bf16 v[28:31], v[32:35], v[212:215], v[28:31]
	v_mfma_f32_16x16x32_bf16 v[24:27], v[44:47], v[212:215], v[24:27]
	v_mfma_f32_16x16x32_bf16 v[12:15], v[32:35], v[226:229], v[12:15]
	v_mfma_f32_16x16x32_bf16 v[8:11], v[44:47], v[226:229], v[8:11]
	v_mfma_f32_16x16x32_bf16 v[76:79], v[36:39], v[200:203], v[76:79]
	v_mfma_f32_16x16x32_bf16 v[72:75], v[48:51], v[200:203], v[72:75]
	v_mfma_f32_16x16x32_bf16 v[60:63], v[36:39], v[208:211], v[60:63]
	v_mfma_f32_16x16x32_bf16 v[56:59], v[48:51], v[208:211], v[56:59]
	v_mfma_f32_16x16x32_bf16 v[28:31], v[36:39], v[216:219], v[28:31]
	v_mfma_f32_16x16x32_bf16 v[24:27], v[48:51], v[216:219], v[24:27]
	v_mfma_f32_16x16x32_bf16 v[12:15], v[36:39], v[232:235], v[12:15]
	v_mfma_f32_16x16x32_bf16 v[8:11], v[48:51], v[232:235], v[8:11]
	v_mfma_f32_16x16x32_bf16 v[40:43], v[166:169], v[204:207], v[40:43]
	v_mfma_f32_16x16x32_bf16 v[20:23], v[158:161], v[212:215], v[20:23]
	v_mfma_f32_16x16x32_bf16 v[16:19], v[166:169], v[212:215], v[16:19]
	v_mfma_f32_16x16x32_bf16 v[4:7], v[158:161], v[226:229], v[4:7]
	v_mfma_f32_16x16x32_bf16 v[0:3], v[166:169], v[226:229], v[0:3]
	v_mfma_f32_16x16x32_bf16 v[32:35], v[158:161], v[182:185], v[68:71]
	v_mfma_f32_16x16x32_bf16 v[36:39], v[166:169], v[182:185], v[64:67]
	v_mfma_f32_16x16x32_bf16 v[44:47], v[158:161], v[204:207], v[52:55]
	v_mfma_f32_16x16x32_bf16 v[40:43], v[170:173], v[208:211], v[40:43]
	v_mfma_f32_16x16x32_bf16 v[20:23], v[162:165], v[216:219], v[20:23]
	v_mfma_f32_16x16x32_bf16 v[16:19], v[170:173], v[216:219], v[16:19]
	v_mfma_f32_16x16x32_bf16 v[4:7], v[162:165], v[232:235], v[4:7]
	v_mfma_f32_16x16x32_bf16 v[0:3], v[170:173], v[232:235], v[0:3]
	v_mfma_f32_16x16x32_bf16 v[32:35], v[162:165], v[200:203], v[32:35]
	v_mfma_f32_16x16x32_bf16 v[36:39], v[170:173], v[200:203], v[36:39]
	s_barrier
	v_mfma_f32_16x16x32_bf16 v[44:47], v[162:165], v[208:211], v[44:47]
	s_setprio 0
	v_or_b32_e32 v48, 0x18000, v194
	v_add_u32_e32 v52, 0x18400, v194
	v_add_u32_e32 v64, 0x18800, v194
	v_add_u32_e32 v68, 0x18c00, v194
	v_or_b32_e32 v81, 0x1c000, v194
	v_add_u32_e32 v162, 0x1c400, v194
	ds_read_b128 v[48:51], v48
	ds_read_b128 v[52:55], v52
	ds_read_b128 v[64:67], v64
	ds_read_b128 v[68:71], v68
	ds_read_b128 v[158:161], v81
	ds_read_b128 v[162:165], v162
	v_add_u32_e32 v81, 0x1c800, v194
	v_add_u32_e32 v170, 0x1cc00, v194
	ds_read_b128 v[166:169], v81
	ds_read_b128 v[170:173], v170
	s_add_u32 s58, s88, 0x40000
	s_addc_u32 s59, s89, 0
	s_mov_b32 m0, s57
	v_lshl_add_u64 v[238:239], s[58:59], 0, v[146:147]
	ds_read_b128 v[182:185], v177 offset:32768
	ds_read_b128 v[200:203], v177 offset:33792
	ds_read_b128 v[204:207], v177 offset:34816
	ds_read_b128 v[208:211], v177 offset:35840
	ds_read_b128 v[212:215], v177 offset:36864
	ds_read_b128 v[216:219], v177 offset:37888
	ds_read_b128 v[226:229], v177 offset:38912
	ds_read_b128 v[232:235], v177 offset:39936
	global_load_lds_dwordx4 v[238:239], off
	v_lshl_add_u64 v[238:239], s[58:59], 0, v[150:151]
	s_mov_b32 m0, s52
	s_nop 0
	global_load_lds_dwordx4 v[238:239], off
	s_waitcnt vmcnt(8)
	s_waitcnt lgkmcnt(0)
	s_barrier
	s_setprio 1
	s_waitcnt lgkmcnt(0)
	v_mfma_f32_16x16x32_bf16 v[142:145], v[48:51], v[182:185], v[142:145]
	v_mfma_f32_16x16x32_bf16 v[138:141], v[64:67], v[182:185], v[138:141]
	v_mfma_f32_16x16x32_bf16 v[126:129], v[48:51], v[204:207], v[126:129]
	v_mfma_f32_16x16x32_bf16 v[122:125], v[64:67], v[204:207], v[122:125]
	v_mfma_f32_16x16x32_bf16 v[110:113], v[48:51], v[212:215], v[110:113]
	v_mfma_f32_16x16x32_bf16 v[106:109], v[64:67], v[212:215], v[106:109]
	v_mfma_f32_16x16x32_bf16 v[94:97], v[48:51], v[226:229], v[94:97]
	v_mfma_f32_16x16x32_bf16 v[90:93], v[64:67], v[226:229], v[90:93]
	v_mfma_f32_16x16x32_bf16 v[142:145], v[52:55], v[200:203], v[142:145]
	v_mfma_f32_16x16x32_bf16 v[138:141], v[68:71], v[200:203], v[138:141]
	v_mfma_f32_16x16x32_bf16 v[126:129], v[52:55], v[208:211], v[126:129]
	v_mfma_f32_16x16x32_bf16 v[122:125], v[68:71], v[208:211], v[122:125]
	v_mfma_f32_16x16x32_bf16 v[110:113], v[52:55], v[216:219], v[110:113]
	v_mfma_f32_16x16x32_bf16 v[106:109], v[68:71], v[216:219], v[106:109]
	v_mfma_f32_16x16x32_bf16 v[94:97], v[52:55], v[232:235], v[94:97]
	v_mfma_f32_16x16x32_bf16 v[90:93], v[68:71], v[232:235], v[90:93]
	v_mfma_f32_16x16x32_bf16 v[134:137], v[158:161], v[182:185], v[134:137]
	v_mfma_f32_16x16x32_bf16 v[130:133], v[166:169], v[182:185], v[130:133]
	v_mfma_f32_16x16x32_bf16 v[118:121], v[158:161], v[204:207], v[118:121]
	v_mfma_f32_16x16x32_bf16 v[114:117], v[166:169], v[204:207], v[114:117]
	v_mfma_f32_16x16x32_bf16 v[102:105], v[158:161], v[212:215], v[102:105]
	v_mfma_f32_16x16x32_bf16 v[98:101], v[166:169], v[212:215], v[98:101]
	v_mfma_f32_16x16x32_bf16 v[86:89], v[158:161], v[226:229], v[86:89]
	v_mfma_f32_16x16x32_bf16 v[82:85], v[166:169], v[226:229], v[82:85]
	v_mfma_f32_16x16x32_bf16 v[134:137], v[162:165], v[200:203], v[134:137]
	v_mfma_f32_16x16x32_bf16 v[130:133], v[170:173], v[200:203], v[130:133]
	v_mfma_f32_16x16x32_bf16 v[118:121], v[162:165], v[208:211], v[118:121]
	v_mfma_f32_16x16x32_bf16 v[114:117], v[170:173], v[208:211], v[114:117]
	v_mfma_f32_16x16x32_bf16 v[102:105], v[162:165], v[216:219], v[102:105]
	v_mfma_f32_16x16x32_bf16 v[98:101], v[170:173], v[216:219], v[98:101]
	v_mfma_f32_16x16x32_bf16 v[86:89], v[162:165], v[232:235], v[86:89]
	s_barrier
; #define PG8_STAGE(bufoff, gbase, voff) do { _Pragma("unroll") for (int _i = 0; _i < 2; ++_i) \
;         __builtin_amdgcn_global_load_lds((const unsigned*)((const char*)(gbase) + (voff)[_i]), (PG8_LAS unsigned*)(lds + (bufoff) + ldsw + _i * 8192), 16, 0, 0); } while (0)
; #define PG8_LDA(dst, b, h) do { _Pragma("unroll") for (int m = 0; m < 4; ++m) _Pragma("unroll") for (int k = 0; k < 2; ++k) dst[m][k] = *(const PG8_LAS bf16x8*)(lds + PG8_SA(b, h) + aoff + m * 2048 + k * 1024); } while (0)
; #define PG8_MMA(ai, bj, At, Bt) do { __builtin_amdgcn_s_setprio(1); _Pragma("unroll") for (int m = 0; m < 4; ++m) _Pragma("unroll") for (int n = 0; n < 2; ++n) _Pragma("unroll") for (int k = 0; k < 2; ++k) \
;         acc[ai][bj][m][n] = __builtin_amdgcn_mfma_f32_16x16x32_bf16(Bt[n][k], At[m][k], acc[ai][bj][m][n], 0, 0, 0); __builtin_amdgcn_s_setprio(0); } while (0)
; #define PG8_WAIT_V(n) asm volatile("s_waitcnt vmcnt(" #n ")" ::: "memory")
; #define PG8_WAIT_L(n) asm volatile("s_waitcnt lgkmcnt(" #n ")" ::: "memory")
; #define PG8_BAR __builtin_amdgcn_s_barrier()
; #define PG8_SCHED __builtin_amdgcn_sched_barrier(0)
; template <class Epi, class Sched, bool ALIGN_EPI = false, bool SP2 = false>
; __device__ __forceinline__ void gemm_phase(PG8_LAS unsigned char* lds, const Gemm g, const Sched& S, const Epi& E, int tid_in) {
;     ...
;             PG8_WAIT_V(8); PG8_WAIT_L(0); PG8_BAR; PG8_MMA(0, 0, At, B0); PG8_MMA(0, 1, At, B1); PG8_BAR; PG8_SCHED;
;             PG8_LDA(At, 1, 1); PG8_STAGE(PG8_SB(1, 0), b3, voffB); PG8_STAGE(PG8_SB(1, 1), b3 + hstep, voffB); PG8_STAGE(PG8_SA(1, 0), a3, voffA);
;             PG8_WAIT_V(8); PG8_WAIT_L(0); PG8_BAR; PG8_MMA(1, 0, At, B0); PG8_MMA(1, 1, At, B1); PG8_BAR; PG8_SCHED;
;     ...
;         if constexpr (ALIGN_EPI) { if (wr == 0) PG8_BAR; }
	v_mfma_f32_16x16x32_bf16 v[82:85], v[170:173], v[232:235], v[82:85]
	s_setprio 0
	s_mov_b32 m0, s67
	v_lshl_add_u64 v[174:175], v[174:175], 0, s[48:49]
	s_add_u32 s58, s86, 0x40080
	ds_read_b128 v[182:185], v177 offset:49152
	ds_read_b128 v[200:203], v177 offset:50176
	ds_read_b128 v[204:207], v177 offset:51200
	ds_read_b128 v[208:211], v177 offset:52224
	ds_read_b128 v[212:215], v177 offset:53248
	ds_read_b128 v[216:219], v177 offset:54272
	ds_read_b128 v[226:229], v177 offset:55296
	ds_read_b128 v[232:235], v177 offset:56320
	global_load_lds_dwordx4 v[174:175], off
	v_lshl_add_u64 v[174:175], v[178:179], 0, s[48:49]
	s_mov_b32 m0, s91
	s_addc_u32 s59, s87, 0
	global_load_lds_dwordx4 v[174:175], off
	v_lshl_add_u64 v[174:175], s[58:59], 0, v[148:149]
	s_mov_b32 m0, s75
	s_nop 0
	global_load_lds_dwordx4 v[174:175], off
	v_lshl_add_u64 v[174:175], s[58:59], 0, v[152:153]
	s_mov_b32 m0, s74
	s_nop 0
	global_load_lds_dwordx4 v[174:175], off
	v_lshl_add_u64 v[174:175], v[180:181], 0, s[48:49]
	s_mov_b32 m0, s53
	s_nop 0
	global_load_lds_dwordx4 v[174:175], off
	v_lshl_add_u64 v[174:175], v[236:237], 0, s[48:49]
	s_mov_b32 m0, s66
	s_nop 0
	global_load_lds_dwordx4 v[174:175], off
	s_waitcnt vmcnt(8)
	s_waitcnt lgkmcnt(0)
	s_barrier
	s_setprio 1
	s_waitcnt lgkmcnt(0)
	v_mfma_f32_16x16x32_bf16 v[76:79], v[48:51], v[182:185], v[76:79]
	v_mfma_f32_16x16x32_bf16 v[72:75], v[64:67], v[182:185], v[72:75]
	v_mfma_f32_16x16x32_bf16 v[60:63], v[48:51], v[204:207], v[60:63]
	v_mfma_f32_16x16x32_bf16 v[56:59], v[64:67], v[204:207], v[56:59]
	v_mfma_f32_16x16x32_bf16 v[28:31], v[48:51], v[212:215], v[28:31]
	v_mfma_f32_16x16x32_bf16 v[24:27], v[64:67], v[212:215], v[24:27]
	v_mfma_f32_16x16x32_bf16 v[12:15], v[48:51], v[226:229], v[12:15]
	v_mfma_f32_16x16x32_bf16 v[8:11], v[64:67], v[226:229], v[8:11]
	v_mfma_f32_16x16x32_bf16 v[76:79], v[52:55], v[200:203], v[76:79]
	v_mfma_f32_16x16x32_bf16 v[72:75], v[68:71], v[200:203], v[72:75]
	v_mfma_f32_16x16x32_bf16 v[60:63], v[52:55], v[208:211], v[60:63]
	v_mfma_f32_16x16x32_bf16 v[56:59], v[68:71], v[208:211], v[56:59]
	v_mfma_f32_16x16x32_bf16 v[28:31], v[52:55], v[216:219], v[28:31]
	v_mfma_f32_16x16x32_bf16 v[24:27], v[68:71], v[216:219], v[24:27]
	v_mfma_f32_16x16x32_bf16 v[12:15], v[52:55], v[232:235], v[12:15]
	v_mfma_f32_16x16x32_bf16 v[8:11], v[68:71], v[232:235], v[8:11]
	v_mfma_f32_16x16x32_bf16 v[32:35], v[158:161], v[182:185], v[32:35]
	v_mfma_f32_16x16x32_bf16 v[68:71], v[162:165], v[200:203], v[32:35]
	v_mfma_f32_16x16x32_bf16 v[32:35], v[166:169], v[182:185], v[36:39]
	v_mfma_f32_16x16x32_bf16 v[64:67], v[170:173], v[200:203], v[32:35]
	v_mfma_f32_16x16x32_bf16 v[32:35], v[158:161], v[204:207], v[44:47]
	v_mfma_f32_16x16x32_bf16 v[52:55], v[162:165], v[208:211], v[32:35]
	v_mfma_f32_16x16x32_bf16 v[32:35], v[166:169], v[204:207], v[40:43]
	v_mfma_f32_16x16x32_bf16 v[20:23], v[158:161], v[212:215], v[20:23]
	v_mfma_f32_16x16x32_bf16 v[16:19], v[166:169], v[212:215], v[16:19]
	v_mfma_f32_16x16x32_bf16 v[4:7], v[158:161], v[226:229], v[4:7]
	v_mfma_f32_16x16x32_bf16 v[0:3], v[166:169], v[226:229], v[0:3]
	v_mfma_f32_16x16x32_bf16 v[40:43], v[170:173], v[208:211], v[32:35]
	v_mfma_f32_16x16x32_bf16 v[20:23], v[162:165], v[216:219], v[20:23]
	v_mfma_f32_16x16x32_bf16 v[16:19], v[170:173], v[216:219], v[16:19]
	v_mfma_f32_16x16x32_bf16 v[4:7], v[162:165], v[232:235], v[4:7]
	s_barrier
	v_mfma_f32_16x16x32_bf16 v[0:3], v[170:173], v[232:235], v[0:3]
	s_setprio 0
	s_add_i32 s27, s27, 2
	s_add_u32 s84, s84, 0x100
	s_addc_u32 s85, s85, 0
	s_add_u32 s25, s25, 0x100
	s_addc_u32 s26, s26, 0
	s_cmp_gt_u32 s27, 13
	s_cbranch_scc0 .LBB0_158
	v_readlane_b32 s22, v254, 30
	v_readlane_b32 s23, v254, 31
	s_and_b64 vcc, exec, s[22:23]
	s_cbranch_vccz .LBB0_161
	s_barrier

; #define PG8_STAGE(bufoff, gbase, voff) do { _Pragma("unroll") for (int _i = 0; _i < 2; ++_i) \
;         __builtin_amdgcn_global_load_lds((const unsigned*)((const char*)(gbase) + (voff)[_i]), (PG8_LAS unsigned*)(lds + (bufoff) + ldsw + _i * 8192), 16, 0, 0); } while (0)
; #define PG8_LDA(dst, b, h) do { _Pragma("unroll") for (int m = 0; m < 4; ++m) _Pragma("unroll") for (int k = 0; k < 2; ++k) dst[m][k] = *(const PG8_LAS bf16x8*)(lds + PG8_SA(b, h) + aoff + m * 2048 + k * 1024); } while (0)
; #define PG8_LDB(dst, b, h) do { _Pragma("unroll") for (int n = 0; n < 2; ++n) _Pragma("unroll") for (int k = 0; k < 2; ++k) dst[n][k] = *(const PG8_LAS bf16x8*)(lds + PG8_SB(b, h) + boff + n * 2048 + k * 1024); } while (0)
; #define PG8_MMA(ai, bj, At, Bt) do { __builtin_amdgcn_s_setprio(1); _Pragma("unroll") for (int m = 0; m < 4; ++m) _Pragma("unroll") for (int n = 0; n < 2; ++n) _Pragma("unroll") for (int k = 0; k < 2; ++k) \
;         acc[ai][bj][m][n] = __builtin_amdgcn_mfma_f32_16x16x32_bf16(Bt[n][k], At[m][k], acc[ai][bj][m][n], 0, 0, 0); __builtin_amdgcn_s_setprio(0); } while (0)
; #define PG8_WAIT_V(n) asm volatile("s_waitcnt vmcnt(" #n ")" ::: "memory")
; #define PG8_WAIT_L(n) asm volatile("s_waitcnt lgkmcnt(" #n ")" ::: "memory")
; #define PG8_BAR __builtin_amdgcn_s_barrier()
; #define PG8_SCHED __builtin_amdgcn_sched_barrier(0)
; template <class Epi, class Sched, bool ALIGN_EPI = false, bool SP2 = false>
; __device__ __forceinline__ void gemm_phase(PG8_LAS unsigned char* lds, const Gemm g, const Sched& S, const Epi& E, int tid_in) {
;     ...
;             PG8_LDB(B0, 0, 0); PG8_LDB(B1, 0, 1); PG8_SCHED; PG8_LDA(At, 0, 0); PG8_STAGE(PG8_SA(1, 1), a1 + hstep, voffA);
;             PG8_WAIT_V(8); PG8_WAIT_L(0); PG8_BAR; PG8_MMA(0, 0, At, B0); PG8_MMA(0, 1, At, B1); PG8_BAR; PG8_SCHED;
;             PG8_LDA(At, 0, 1); PG8_STAGE(PG8_SB(0, 0), b2, voffB); PG8_STAGE(PG8_SB(0, 1), b2 + hstep, voffB); PG8_STAGE(PG8_SA(0, 0), a2, voffA);
;             PG8_WAIT_V(8); PG8_WAIT_L(0); PG8_BAR; PG8_MMA(1, 0, At, B0); PG8_MMA(1, 1, At, B1); PG8_BAR; PG8_SCHED;
.LBB0_440:
	v_or_b32_e32 v130, 0x10000, v248
	v_add_u32_e32 v134, 0x10400, v248
	v_add_u32_e32 v138, 0x10800, v248
	v_add_u32_e32 v142, 0x10c00, v248
	v_or_b32_e32 v146, 0x14000, v248
	v_add_u32_e32 v150, 0x14400, v248
	v_add_u32_e32 v154, 0x14800, v248
	v_add_u32_e32 v158, 0x14c00, v248
	ds_read_b128 v[130:133], v130
	ds_read_b128 v[134:137], v134
	ds_read_b128 v[138:141], v138
	ds_read_b128 v[142:145], v142
	ds_read_b128 v[146:149], v146
	ds_read_b128 v[150:153], v150
	ds_read_b128 v[154:157], v154
	ds_read_b128 v[158:161], v158
	s_add_u32 s80, s78, 0xfffc0080
	s_addc_u32 s81, s79, -1
	s_cmp_eq_u32 s87, 12
	s_cselect_b32 s83, s71, s81
	s_cselect_b32 s82, s77, s80
	s_cselect_b32 s81, s67, s86
	s_cselect_b32 s80, s84, s85
	v_lshl_add_u64 v[178:179], s[78:79], 0, v[202:203]
	s_add_i32 m0, s57, 0xc000
	ds_read_b128 v[162:165], v247
	ds_read_b128 v[166:169], v247 offset:1024
	ds_read_b128 v[170:173], v247 offset:2048
	ds_read_b128 v[174:177], v247 offset:3072
	ds_read_b128 v[182:185], v247 offset:4096
	ds_read_b128 v[212:215], v247 offset:5120
	ds_read_b128 v[226:229], v247 offset:6144
	ds_read_b128 v[232:235], v247 offset:7168
	global_load_lds_dwordx4 v[178:179], off
	v_lshl_add_u64 v[178:179], s[78:79], 0, v[204:205]
	s_add_i32 m0, s57, 0xe000
	s_nop 0
	global_load_lds_dwordx4 v[178:179], off
	s_waitcnt vmcnt(8)
	s_waitcnt lgkmcnt(0)
	s_barrier
	s_setprio 1
	s_waitcnt lgkmcnt(0)
	v_mfma_f32_16x16x32_bf16 v[126:129], v[130:133], v[162:165], v[126:129]
	v_mfma_f32_16x16x32_bf16 v[122:125], v[138:141], v[162:165], v[122:125]
	v_mfma_f32_16x16x32_bf16 v[114:117], v[130:133], v[170:173], v[114:117]
	v_mfma_f32_16x16x32_bf16 v[106:109], v[138:141], v[170:173], v[106:109]
	v_mfma_f32_16x16x32_bf16 v[98:101], v[130:133], v[182:185], v[98:101]
	v_mfma_f32_16x16x32_bf16 v[90:93], v[138:141], v[182:185], v[90:93]
	v_mfma_f32_16x16x32_bf16 v[76:79], v[130:133], v[226:229], v[76:79]
	v_mfma_f32_16x16x32_bf16 v[72:75], v[138:141], v[226:229], v[72:75]
	v_mfma_f32_16x16x32_bf16 v[126:129], v[134:137], v[166:169], v[126:129]
	v_mfma_f32_16x16x32_bf16 v[122:125], v[142:145], v[166:169], v[122:125]
	v_mfma_f32_16x16x32_bf16 v[114:117], v[134:137], v[174:177], v[114:117]
	v_mfma_f32_16x16x32_bf16 v[106:109], v[142:145], v[174:177], v[106:109]
	v_mfma_f32_16x16x32_bf16 v[98:101], v[134:137], v[212:215], v[98:101]
	v_mfma_f32_16x16x32_bf16 v[90:93], v[142:145], v[212:215], v[90:93]
	v_mfma_f32_16x16x32_bf16 v[76:79], v[134:137], v[232:235], v[76:79]
	v_mfma_f32_16x16x32_bf16 v[72:75], v[142:145], v[232:235], v[72:75]
	v_mfma_f32_16x16x32_bf16 v[118:121], v[146:149], v[162:165], v[118:121]
	v_mfma_f32_16x16x32_bf16 v[110:113], v[154:157], v[162:165], v[110:113]
	v_mfma_f32_16x16x32_bf16 v[102:105], v[146:149], v[170:173], v[102:105]
	v_mfma_f32_16x16x32_bf16 v[94:97], v[154:157], v[170:173], v[94:97]
	v_mfma_f32_16x16x32_bf16 v[86:89], v[146:149], v[182:185], v[86:89]
	v_mfma_f32_16x16x32_bf16 v[82:85], v[154:157], v[182:185], v[82:85]
	v_mfma_f32_16x16x32_bf16 v[68:71], v[146:149], v[226:229], v[68:71]
	v_mfma_f32_16x16x32_bf16 v[64:67], v[154:157], v[226:229], v[64:67]
	v_mfma_f32_16x16x32_bf16 v[118:121], v[150:153], v[166:169], v[118:121]
	v_mfma_f32_16x16x32_bf16 v[110:113], v[158:161], v[166:169], v[110:113]
	v_mfma_f32_16x16x32_bf16 v[102:105], v[150:153], v[174:177], v[102:105]
	v_mfma_f32_16x16x32_bf16 v[94:97], v[158:161], v[174:177], v[94:97]
	v_mfma_f32_16x16x32_bf16 v[86:89], v[150:153], v[212:215], v[86:89]
	v_mfma_f32_16x16x32_bf16 v[82:85], v[158:161], v[212:215], v[82:85]
	v_mfma_f32_16x16x32_bf16 v[68:71], v[150:153], v[232:235], v[68:71]
	s_barrier
	v_mfma_f32_16x16x32_bf16 v[64:67], v[158:161], v[232:235], v[64:67]
	s_setprio 0
	s_mov_b32 m0, s20
	v_lshl_add_u64 v[178:179], s[80:81], 0, v[198:199]
	s_add_u32 s88, s80, 0x40000
	ds_read_b128 v[162:165], v247 offset:16384
	ds_read_b128 v[166:169], v247 offset:17408
	ds_read_b128 v[170:173], v247 offset:18432
	ds_read_b128 v[174:177], v247 offset:19456
	ds_read_b128 v[182:185], v247 offset:20480
	ds_read_b128 v[212:215], v247 offset:21504
	ds_read_b128 v[226:229], v247 offset:22528
	ds_read_b128 v[232:235], v247 offset:23552
	global_load_lds_dwordx4 v[178:179], off
	v_lshl_add_u64 v[180:181], s[80:81], 0, v[194:195]
	s_mov_b32 m0, s21
	s_addc_u32 s89, s81, 0
	global_load_lds_dwordx4 v[180:181], off
	v_lshl_add_u64 v[208:209], s[88:89], 0, v[198:199]
	s_mov_b32 m0, s22
	v_lshl_add_u64 v[218:219], s[82:83], 0, v[196:197]
	global_load_lds_dwordx4 v[208:209], off
	v_lshl_add_u64 v[208:209], s[88:89], 0, v[194:195]
	s_mov_b32 m0, s23
	s_nop 0
	global_load_lds_dwordx4 v[208:209], off
	v_lshl_add_u64 v[208:209], s[82:83], 0, v[200:201]
	s_mov_b32 m0, s57
	s_nop 0
	global_load_lds_dwordx4 v[208:209], off
	s_mov_b32 m0, s24
	s_nop 0
	global_load_lds_dwordx4 v[218:219], off
	s_waitcnt vmcnt(8)
	s_waitcnt lgkmcnt(0)
	s_barrier
; #define PG8_STAGE(bufoff, gbase, voff) do { _Pragma("unroll") for (int _i = 0; _i < 2; ++_i) \
;         __builtin_amdgcn_global_load_lds((const unsigned*)((const char*)(gbase) + (voff)[_i]), (PG8_LAS unsigned*)(lds + (bufoff) + ldsw + _i * 8192), 16, 0, 0); } while (0)
; #define PG8_LDA(dst, b, h) do { _Pragma("unroll") for (int m = 0; m < 4; ++m) _Pragma("unroll") for (int k = 0; k < 2; ++k) dst[m][k] = *(const PG8_LAS bf16x8*)(lds + PG8_SA(b, h) + aoff + m * 2048 + k * 1024); } while (0)
; #define PG8_LDB(dst, b, h) do { _Pragma("unroll") for (int n = 0; n < 2; ++n) _Pragma("unroll") for (int k = 0; k < 2; ++k) dst[n][k] = *(const PG8_LAS bf16x8*)(lds + PG8_SB(b, h) + boff + n * 2048 + k * 1024); } while (0)
; #define PG8_MMA(ai, bj, At, Bt) do { __builtin_amdgcn_s_setprio(1); _Pragma("unroll") for (int m = 0; m < 4; ++m) _Pragma("unroll") for (int n = 0; n < 2; ++n) _Pragma("unroll") for (int k = 0; k < 2; ++k) \
;         acc[ai][bj][m][n] = __builtin_amdgcn_mfma_f32_16x16x32_bf16(Bt[n][k], At[m][k], acc[ai][bj][m][n], 0, 0, 0); __builtin_amdgcn_s_setprio(0); } while (0)
; #define PG8_WAIT_V(n) asm volatile("s_waitcnt vmcnt(" #n ")" ::: "memory")
; #define PG8_WAIT_L(n) asm volatile("s_waitcnt lgkmcnt(" #n ")" ::: "memory")
; #define PG8_BAR __builtin_amdgcn_s_barrier()
; #define PG8_SCHED __builtin_amdgcn_sched_barrier(0)
; template <class Epi, class Sched, bool ALIGN_EPI = false, bool SP2 = false>
; __device__ __forceinline__ void gemm_phase(PG8_LAS unsigned char* lds, const Gemm g, const Sched& S, const Epi& E, int tid_in) {
;     ...
;             PG8_WAIT_V(8); PG8_WAIT_L(0); PG8_BAR; PG8_MMA(1, 0, At, B0); PG8_MMA(1, 1, At, B1); PG8_BAR; PG8_SCHED;
;             PG8_LDB(B0, 1, 0); PG8_LDB(B1, 1, 1); PG8_SCHED; PG8_LDA(At, 1, 0); PG8_STAGE(PG8_SA(0, 1), a2 + hstep, voffA);
;             PG8_WAIT_V(8); PG8_WAIT_L(0); PG8_BAR; PG8_MMA(0, 0, At, B0); PG8_MMA(0, 1, At, B1); PG8_BAR; PG8_SCHED;
	s_setprio 1
	s_waitcnt lgkmcnt(0)
	v_mfma_f32_16x16x32_bf16 v[60:63], v[130:133], v[162:165], v[60:63]
	v_mfma_f32_16x16x32_bf16 v[56:59], v[138:141], v[162:165], v[56:59]
	v_mfma_f32_16x16x32_bf16 v[44:47], v[130:133], v[170:173], v[44:47]
	v_mfma_f32_16x16x32_bf16 v[40:43], v[138:141], v[170:173], v[40:43]
	v_mfma_f32_16x16x32_bf16 v[28:31], v[130:133], v[182:185], v[28:31]
	v_mfma_f32_16x16x32_bf16 v[24:27], v[138:141], v[182:185], v[24:27]
	v_mfma_f32_16x16x32_bf16 v[12:15], v[130:133], v[226:229], v[12:15]
	v_mfma_f32_16x16x32_bf16 v[8:11], v[138:141], v[226:229], v[8:11]
	v_mfma_f32_16x16x32_bf16 v[60:63], v[134:137], v[166:169], v[60:63]
	v_mfma_f32_16x16x32_bf16 v[56:59], v[142:145], v[166:169], v[56:59]
	v_mfma_f32_16x16x32_bf16 v[44:47], v[134:137], v[174:177], v[44:47]
	v_mfma_f32_16x16x32_bf16 v[40:43], v[142:145], v[174:177], v[40:43]
	v_mfma_f32_16x16x32_bf16 v[28:31], v[134:137], v[212:215], v[28:31]
	v_mfma_f32_16x16x32_bf16 v[24:27], v[142:145], v[212:215], v[24:27]
	v_mfma_f32_16x16x32_bf16 v[12:15], v[134:137], v[232:235], v[12:15]
	v_mfma_f32_16x16x32_bf16 v[8:11], v[142:145], v[232:235], v[8:11]
	v_mfma_f32_16x16x32_bf16 v[52:55], v[146:149], v[162:165], v[52:55]
	v_mfma_f32_16x16x32_bf16 v[48:51], v[154:157], v[162:165], v[48:51]
	v_mfma_f32_16x16x32_bf16 v[36:39], v[146:149], v[170:173], v[36:39]
	v_mfma_f32_16x16x32_bf16 v[32:35], v[154:157], v[170:173], v[32:35]
	v_mfma_f32_16x16x32_bf16 v[20:23], v[146:149], v[182:185], v[20:23]
	v_mfma_f32_16x16x32_bf16 v[16:19], v[154:157], v[182:185], v[16:19]
	v_mfma_f32_16x16x32_bf16 v[4:7], v[146:149], v[226:229], v[4:7]
	v_mfma_f32_16x16x32_bf16 v[0:3], v[154:157], v[226:229], v[0:3]
	v_mfma_f32_16x16x32_bf16 v[52:55], v[150:153], v[166:169], v[52:55]
	v_mfma_f32_16x16x32_bf16 v[48:51], v[158:161], v[166:169], v[48:51]
	v_mfma_f32_16x16x32_bf16 v[36:39], v[150:153], v[174:177], v[36:39]
	v_mfma_f32_16x16x32_bf16 v[32:35], v[158:161], v[174:177], v[32:35]
	v_mfma_f32_16x16x32_bf16 v[20:23], v[150:153], v[212:215], v[20:23]
	v_mfma_f32_16x16x32_bf16 v[16:19], v[158:161], v[212:215], v[16:19]
	v_mfma_f32_16x16x32_bf16 v[4:7], v[150:153], v[232:235], v[4:7]
	s_barrier
	v_mfma_f32_16x16x32_bf16 v[0:3], v[158:161], v[232:235], v[0:3]
	s_setprio 0
	v_or_b32_e32 v130, 0x18000, v248
	v_add_u32_e32 v134, 0x18400, v248
	v_add_u32_e32 v138, 0x18800, v248
	v_add_u32_e32 v142, 0x18c00, v248
	v_or_b32_e32 v146, 0x1c000, v248
	v_add_u32_e32 v150, 0x1c400, v248
	v_add_u32_e32 v154, 0x1c800, v248
	v_add_u32_e32 v158, 0x1cc00, v248
	ds_read_b128 v[130:133], v130
	ds_read_b128 v[134:137], v134
	ds_read_b128 v[138:141], v138
	ds_read_b128 v[142:145], v142
	ds_read_b128 v[146:149], v146
	ds_read_b128 v[150:153], v150
	ds_read_b128 v[154:157], v154
	ds_read_b128 v[158:161], v158
	s_add_u32 s82, s82, 0x40000
	s_addc_u32 s83, s83, 0
	s_mov_b32 m0, s25
	v_lshl_add_u64 v[236:237], s[82:83], 0, v[200:201]
	ds_read_b128 v[162:165], v247 offset:32768
	ds_read_b128 v[166:169], v247 offset:33792
	ds_read_b128 v[170:173], v247 offset:34816
	ds_read_b128 v[174:177], v247 offset:35840
	ds_read_b128 v[182:185], v247 offset:36864
	ds_read_b128 v[212:215], v247 offset:37888
	ds_read_b128 v[226:229], v247 offset:38912
	ds_read_b128 v[232:235], v247 offset:39936
	global_load_lds_dwordx4 v[236:237], off
	v_lshl_add_u64 v[236:237], s[82:83], 0, v[196:197]
	s_mov_b32 m0, s26
	s_nop 0
	global_load_lds_dwordx4 v[236:237], off
	s_waitcnt vmcnt(8)
	s_waitcnt lgkmcnt(0)
	s_barrier
	s_setprio 1
	s_waitcnt lgkmcnt(0)
	v_mfma_f32_16x16x32_bf16 v[126:129], v[130:133], v[162:165], v[126:129]
	v_mfma_f32_16x16x32_bf16 v[122:125], v[138:141], v[162:165], v[122:125]
	v_mfma_f32_16x16x32_bf16 v[114:117], v[130:133], v[170:173], v[114:117]
	v_mfma_f32_16x16x32_bf16 v[106:109], v[138:141], v[170:173], v[106:109]
	v_mfma_f32_16x16x32_bf16 v[98:101], v[130:133], v[182:185], v[98:101]
	v_mfma_f32_16x16x32_bf16 v[90:93], v[138:141], v[182:185], v[90:93]
	v_mfma_f32_16x16x32_bf16 v[76:79], v[130:133], v[226:229], v[76:79]
	v_mfma_f32_16x16x32_bf16 v[72:75], v[138:141], v[226:229], v[72:75]
	v_mfma_f32_16x16x32_bf16 v[126:129], v[134:137], v[166:169], v[126:129]
	v_mfma_f32_16x16x32_bf16 v[122:125], v[142:145], v[166:169], v[122:125]
	v_mfma_f32_16x16x32_bf16 v[114:117], v[134:137], v[174:177], v[114:117]
	v_mfma_f32_16x16x32_bf16 v[106:109], v[142:145], v[174:177], v[106:109]
	v_mfma_f32_16x16x32_bf16 v[98:101], v[134:137], v[212:215], v[98:101]
	v_mfma_f32_16x16x32_bf16 v[90:93], v[142:145], v[212:215], v[90:93]
	v_mfma_f32_16x16x32_bf16 v[76:79], v[134:137], v[232:235], v[76:79]
	v_mfma_f32_16x16x32_bf16 v[72:75], v[142:145], v[232:235], v[72:75]
	v_mfma_f32_16x16x32_bf16 v[118:121], v[146:149], v[162:165], v[118:121]
	v_mfma_f32_16x16x32_bf16 v[110:113], v[154:157], v[162:165], v[110:113]
	v_mfma_f32_16x16x32_bf16 v[102:105], v[146:149], v[170:173], v[102:105]
	v_mfma_f32_16x16x32_bf16 v[94:97], v[154:157], v[170:173], v[94:97]
	v_mfma_f32_16x16x32_bf16 v[86:89], v[146:149], v[182:185], v[86:89]
	v_mfma_f32_16x16x32_bf16 v[82:85], v[154:157], v[182:185], v[82:85]
	v_mfma_f32_16x16x32_bf16 v[68:71], v[146:149], v[226:229], v[68:71]
	v_mfma_f32_16x16x32_bf16 v[64:67], v[154:157], v[226:229], v[64:67]
	v_mfma_f32_16x16x32_bf16 v[118:121], v[150:153], v[166:169], v[118:121]
	v_mfma_f32_16x16x32_bf16 v[110:113], v[158:161], v[166:169], v[110:113]
	v_mfma_f32_16x16x32_bf16 v[102:105], v[150:153], v[174:177], v[102:105]
	v_mfma_f32_16x16x32_bf16 v[94:97], v[158:161], v[174:177], v[94:97]
	v_mfma_f32_16x16x32_bf16 v[86:89], v[150:153], v[212:215], v[86:89]
	v_mfma_f32_16x16x32_bf16 v[82:85], v[158:161], v[212:215], v[82:85]
	v_mfma_f32_16x16x32_bf16 v[68:71], v[150:153], v[232:235], v[68:71]
	s_barrier
; #define PG8_STAGE(bufoff, gbase, voff) do { _Pragma("unroll") for (int _i = 0; _i < 2; ++_i) \
;         __builtin_amdgcn_global_load_lds((const unsigned*)((const char*)(gbase) + (voff)[_i]), (PG8_LAS unsigned*)(lds + (bufoff) + ldsw + _i * 8192), 16, 0, 0); } while (0)
; #define PG8_LDA(dst, b, h) do { _Pragma("unroll") for (int m = 0; m < 4; ++m) _Pragma("unroll") for (int k = 0; k < 2; ++k) dst[m][k] = *(const PG8_LAS bf16x8*)(lds + PG8_SA(b, h) + aoff + m * 2048 + k * 1024); } while (0)
; #define PG8_MMA(ai, bj, At, Bt) do { __builtin_amdgcn_s_setprio(1); _Pragma("unroll") for (int m = 0; m < 4; ++m) _Pragma("unroll") for (int n = 0; n < 2; ++n) _Pragma("unroll") for (int k = 0; k < 2; ++k) \
;         acc[ai][bj][m][n] = __builtin_amdgcn_mfma_f32_16x16x32_bf16(Bt[n][k], At[m][k], acc[ai][bj][m][n], 0, 0, 0); __builtin_amdgcn_s_setprio(0); } while (0)
; #define PG8_WAIT_V(n) asm volatile("s_waitcnt vmcnt(" #n ")" ::: "memory")
; #define PG8_WAIT_L(n) asm volatile("s_waitcnt lgkmcnt(" #n ")" ::: "memory")
; #define PG8_BAR __builtin_amdgcn_s_barrier()
; #define PG8_SCHED __builtin_amdgcn_sched_barrier(0)
; template <class Epi, class Sched, bool ALIGN_EPI = false, bool SP2 = false>
; __device__ __forceinline__ void gemm_phase(PG8_LAS unsigned char* lds, const Gemm g, const Sched& S, const Epi& E, int tid_in) {
;     ...
;             PG8_WAIT_V(8); PG8_WAIT_L(0); PG8_BAR; PG8_MMA(0, 0, At, B0); PG8_MMA(0, 1, At, B1); PG8_BAR; PG8_SCHED;
;             PG8_LDA(At, 1, 1); PG8_STAGE(PG8_SB(1, 0), b3, voffB); PG8_STAGE(PG8_SB(1, 1), b3 + hstep, voffB); PG8_STAGE(PG8_SA(1, 0), a3, voffA);
;             PG8_WAIT_V(8); PG8_WAIT_L(0); PG8_BAR; PG8_MMA(1, 0, At, B0); PG8_MMA(1, 1, At, B1); PG8_BAR; PG8_SCHED;
;     ...
;         if constexpr (ALIGN_EPI) { if (wr == 0) PG8_BAR; }
	v_mfma_f32_16x16x32_bf16 v[64:67], v[158:161], v[232:235], v[64:67]
	s_setprio 0
	s_mov_b32 m0, s27
	v_lshl_add_u64 v[178:179], v[178:179], 0, s[48:49]
	s_add_u32 s80, s80, 0x40080
	ds_read_b128 v[162:165], v247 offset:49152
	ds_read_b128 v[166:169], v247 offset:50176
	ds_read_b128 v[170:173], v247 offset:51200
	ds_read_b128 v[174:177], v247 offset:52224
	ds_read_b128 v[182:185], v247 offset:53248
	ds_read_b128 v[212:215], v247 offset:54272
	ds_read_b128 v[226:229], v247 offset:55296
	ds_read_b128 v[232:235], v247 offset:56320
	global_load_lds_dwordx4 v[178:179], off
	v_lshl_add_u64 v[178:179], v[180:181], 0, s[48:49]
	s_mov_b32 m0, s58
	s_addc_u32 s81, s81, 0
	global_load_lds_dwordx4 v[178:179], off
	v_lshl_add_u64 v[178:179], s[80:81], 0, v[198:199]
	s_mov_b32 m0, s63
	s_nop 0
	global_load_lds_dwordx4 v[178:179], off
	v_lshl_add_u64 v[178:179], s[80:81], 0, v[194:195]
	s_mov_b32 m0, s64
	s_nop 0
	global_load_lds_dwordx4 v[178:179], off
	v_lshl_add_u64 v[178:179], v[208:209], 0, s[48:49]
	s_mov_b32 m0, s59
	s_nop 0
	global_load_lds_dwordx4 v[178:179], off
	v_lshl_add_u64 v[178:179], v[218:219], 0, s[48:49]
	s_mov_b32 m0, s62
	s_nop 0
	global_load_lds_dwordx4 v[178:179], off
	s_waitcnt vmcnt(8)
	s_waitcnt lgkmcnt(0)
	s_barrier
	s_setprio 1
	s_waitcnt lgkmcnt(0)
	v_mfma_f32_16x16x32_bf16 v[60:63], v[130:133], v[162:165], v[60:63]
	v_mfma_f32_16x16x32_bf16 v[56:59], v[138:141], v[162:165], v[56:59]
	v_mfma_f32_16x16x32_bf16 v[44:47], v[130:133], v[170:173], v[44:47]
	v_mfma_f32_16x16x32_bf16 v[40:43], v[138:141], v[170:173], v[40:43]
	v_mfma_f32_16x16x32_bf16 v[28:31], v[130:133], v[182:185], v[28:31]
	v_mfma_f32_16x16x32_bf16 v[24:27], v[138:141], v[182:185], v[24:27]
	v_mfma_f32_16x16x32_bf16 v[12:15], v[130:133], v[226:229], v[12:15]
	v_mfma_f32_16x16x32_bf16 v[8:11], v[138:141], v[226:229], v[8:11]
	v_mfma_f32_16x16x32_bf16 v[60:63], v[134:137], v[166:169], v[60:63]
	v_mfma_f32_16x16x32_bf16 v[56:59], v[142:145], v[166:169], v[56:59]
	v_mfma_f32_16x16x32_bf16 v[44:47], v[134:137], v[174:177], v[44:47]
	v_mfma_f32_16x16x32_bf16 v[40:43], v[142:145], v[174:177], v[40:43]
	v_mfma_f32_16x16x32_bf16 v[28:31], v[134:137], v[212:215], v[28:31]
	v_mfma_f32_16x16x32_bf16 v[24:27], v[142:145], v[212:215], v[24:27]
	v_mfma_f32_16x16x32_bf16 v[12:15], v[134:137], v[232:235], v[12:15]
	v_mfma_f32_16x16x32_bf16 v[8:11], v[142:145], v[232:235], v[8:11]
	v_mfma_f32_16x16x32_bf16 v[52:55], v[146:149], v[162:165], v[52:55]
	v_mfma_f32_16x16x32_bf16 v[48:51], v[154:157], v[162:165], v[48:51]
	v_mfma_f32_16x16x32_bf16 v[36:39], v[146:149], v[170:173], v[36:39]
	v_mfma_f32_16x16x32_bf16 v[32:35], v[154:157], v[170:173], v[32:35]
	v_mfma_f32_16x16x32_bf16 v[20:23], v[146:149], v[182:185], v[20:23]
	v_mfma_f32_16x16x32_bf16 v[16:19], v[154:157], v[182:185], v[16:19]
	v_mfma_f32_16x16x32_bf16 v[4:7], v[146:149], v[226:229], v[4:7]
	v_mfma_f32_16x16x32_bf16 v[0:3], v[154:157], v[226:229], v[0:3]
	v_mfma_f32_16x16x32_bf16 v[52:55], v[150:153], v[166:169], v[52:55]
	v_mfma_f32_16x16x32_bf16 v[48:51], v[158:161], v[166:169], v[48:51]
	v_mfma_f32_16x16x32_bf16 v[36:39], v[150:153], v[174:177], v[36:39]
	v_mfma_f32_16x16x32_bf16 v[32:35], v[158:161], v[174:177], v[32:35]
	v_mfma_f32_16x16x32_bf16 v[20:23], v[150:153], v[212:215], v[20:23]
	v_mfma_f32_16x16x32_bf16 v[16:19], v[158:161], v[212:215], v[16:19]
	v_mfma_f32_16x16x32_bf16 v[4:7], v[150:153], v[232:235], v[4:7]
	s_barrier
	v_mfma_f32_16x16x32_bf16 v[0:3], v[158:161], v[232:235], v[0:3]
	s_setprio 0
	s_add_i32 s87, s87, 2
	s_add_u32 s78, s78, 0x100
	s_addc_u32 s79, s79, 0
	s_add_u32 s85, s85, 0x100
	s_addc_u32 s86, s86, 0
	s_cmp_gt_u32 s87, 13
	s_cbranch_scc0 .LBB0_440
	v_mov_b32_e32 v239, 0x60
	v_mov_b32_e32 v236, 0xc0
	s_and_b64 vcc, exec, s[42:43]
	s_cbranch_vccz .LBB0_443
	s_barrier

; #define PG8_STAGE(bufoff, gbase, voff) do { _Pragma("unroll") for (int _i = 0; _i < 2; ++_i) \
;         __builtin_amdgcn_global_load_lds((const unsigned*)((const char*)(gbase) + (voff)[_i]), (PG8_LAS unsigned*)(lds + (bufoff) + ldsw + _i * 8192), 16, 0, 0); } while (0)
; #define PG8_LDA(dst, b, h) do { _Pragma("unroll") for (int m = 0; m < 4; ++m) _Pragma("unroll") for (int k = 0; k < 2; ++k) dst[m][k] = *(const PG8_LAS bf16x8*)(lds + PG8_SA(b, h) + aoff + m * 2048 + k * 1024); } while (0)
; #define PG8_LDB(dst, b, h) do { _Pragma("unroll") for (int n = 0; n < 2; ++n) _Pragma("unroll") for (int k = 0; k < 2; ++k) dst[n][k] = *(const PG8_LAS bf16x8*)(lds + PG8_SB(b, h) + boff + n * 2048 + k * 1024); } while (0)
; #define PG8_MMA(ai, bj, At, Bt) do { __builtin_amdgcn_s_setprio(1); _Pragma("unroll") for (int m = 0; m < 4; ++m) _Pragma("unroll") for (int n = 0; n < 2; ++n) _Pragma("unroll") for (int k = 0; k < 2; ++k) \
;         acc[ai][bj][m][n] = __builtin_amdgcn_mfma_f32_16x16x32_bf16(Bt[n][k], At[m][k], acc[ai][bj][m][n], 0, 0, 0); __builtin_amdgcn_s_setprio(0); } while (0)
; #define PG8_WAIT_V(n) asm volatile("s_waitcnt vmcnt(" #n ")" ::: "memory")
; #define PG8_WAIT_L(n) asm volatile("s_waitcnt lgkmcnt(" #n ")" ::: "memory")
; #define PG8_BAR __builtin_amdgcn_s_barrier()
; #define PG8_SCHED __builtin_amdgcn_sched_barrier(0)
; template <class Epi, class Sched, bool ALIGN_EPI = false, bool SP2 = false>
; __device__ __forceinline__ void gemm_phase(PG8_LAS unsigned char* lds, const Gemm g, const Sched& S, const Epi& E, int tid_in) {
;     ...
;             PG8_LDB(B0, 0, 0); PG8_LDB(B1, 0, 1); PG8_SCHED; PG8_LDA(At, 0, 0); PG8_STAGE(PG8_SA(1, 1), a1 + hstep, voffA);
;             PG8_WAIT_V(8); PG8_WAIT_L(0); PG8_BAR; PG8_MMA(0, 0, At, B0); PG8_MMA(0, 1, At, B1); PG8_BAR; PG8_SCHED;
;             PG8_LDA(At, 0, 1); PG8_STAGE(PG8_SB(0, 0), b2, voffB); PG8_STAGE(PG8_SB(0, 1), b2 + hstep, voffB); PG8_STAGE(PG8_SA(0, 0), a2, voffA);
;             PG8_WAIT_V(8); PG8_WAIT_L(0); PG8_BAR; PG8_MMA(1, 0, At, B0); PG8_MMA(1, 1, At, B1); PG8_BAR; PG8_SCHED;
.LBB0_508:
	v_or_b32_e32 v40, 0x10000, v215
	v_add_u32_e32 v44, 0x10400, v215
	v_add_u32_e32 v52, 0x10800, v215
	v_add_u32_e32 v60, 0x10c00, v215
	v_or_b32_e32 v146, 0x14000, v215
	v_add_u32_e32 v150, 0x14400, v215
	v_add_u32_e32 v154, 0x14800, v215
	v_add_u32_e32 v158, 0x14c00, v215
	s_add_i32 s44, s42, 2
	ds_read_b128 v[40:43], v40
	ds_read_b128 v[44:47], v44
	ds_read_b128 v[52:55], v52
	ds_read_b128 v[60:63], v60
	ds_read_b128 v[146:149], v146
	ds_read_b128 v[150:153], v150
	ds_read_b128 v[154:157], v154
	ds_read_b128 v[158:161], v158
	s_add_u32 s45, s40, 0x80
	s_addc_u32 s43, s41, 0
	s_cmp_eq_u32 s94, s42
	s_cselect_b32 s42, s88, s45
	s_cselect_b32 s43, s89, s43
	s_cselect_b32 s93, s91, s27
	s_cselect_b32 s92, s90, s26
	v_lshl_add_u64 v[218:219], s[40:41], 0, v[174:175]
	s_add_i32 m0, s57, 0xc000
	ds_read_b128 v[194:197], v214
	ds_read_b128 v[198:201], v214 offset:1024
	ds_read_b128 v[202:205], v214 offset:2048
	ds_read_b128 v[206:209], v214 offset:3072
	ds_read_b128 v[210:213], v214 offset:4096
	ds_read_b128 v[226:229], v214 offset:5120
	ds_read_b128 v[232:235], v214 offset:6144
	ds_read_b128 v[182:185], v214 offset:7168
	global_load_lds_dwordx4 v[218:219], off
	v_lshl_add_u64 v[218:219], s[40:41], 0, v[176:177]
	s_add_i32 m0, s57, 0xe000
	s_nop 0
	global_load_lds_dwordx4 v[218:219], off
	s_waitcnt vmcnt(8)
	s_waitcnt lgkmcnt(0)
	s_barrier
	s_setprio 1
	s_waitcnt lgkmcnt(0)
	v_mfma_f32_16x16x32_bf16 v[142:145], v[40:43], v[194:197], v[142:145]
	v_mfma_f32_16x16x32_bf16 v[138:141], v[52:55], v[194:197], v[138:141]
	v_mfma_f32_16x16x32_bf16 v[126:129], v[40:43], v[202:205], v[126:129]
	v_mfma_f32_16x16x32_bf16 v[122:125], v[52:55], v[202:205], v[122:125]
	v_mfma_f32_16x16x32_bf16 v[110:113], v[40:43], v[210:213], v[110:113]
	v_mfma_f32_16x16x32_bf16 v[106:109], v[52:55], v[210:213], v[106:109]
	v_mfma_f32_16x16x32_bf16 v[94:97], v[40:43], v[232:235], v[94:97]
	v_mfma_f32_16x16x32_bf16 v[90:93], v[52:55], v[232:235], v[90:93]
	v_mfma_f32_16x16x32_bf16 v[142:145], v[44:47], v[198:201], v[142:145]
	v_mfma_f32_16x16x32_bf16 v[138:141], v[60:63], v[198:201], v[138:141]
	v_mfma_f32_16x16x32_bf16 v[126:129], v[44:47], v[206:209], v[126:129]
	v_mfma_f32_16x16x32_bf16 v[122:125], v[60:63], v[206:209], v[122:125]
	v_mfma_f32_16x16x32_bf16 v[110:113], v[44:47], v[226:229], v[110:113]
	v_mfma_f32_16x16x32_bf16 v[106:109], v[60:63], v[226:229], v[106:109]
	v_mfma_f32_16x16x32_bf16 v[94:97], v[44:47], v[182:185], v[94:97]
	v_mfma_f32_16x16x32_bf16 v[90:93], v[60:63], v[182:185], v[90:93]
	v_mfma_f32_16x16x32_bf16 v[134:137], v[146:149], v[194:197], v[134:137]
	v_mfma_f32_16x16x32_bf16 v[130:133], v[154:157], v[194:197], v[130:133]
	v_mfma_f32_16x16x32_bf16 v[118:121], v[146:149], v[202:205], v[118:121]
	v_mfma_f32_16x16x32_bf16 v[114:117], v[154:157], v[202:205], v[114:117]
	v_mfma_f32_16x16x32_bf16 v[102:105], v[146:149], v[210:213], v[102:105]
	v_mfma_f32_16x16x32_bf16 v[98:101], v[154:157], v[210:213], v[98:101]
	v_mfma_f32_16x16x32_bf16 v[86:89], v[146:149], v[232:235], v[86:89]
	v_mfma_f32_16x16x32_bf16 v[82:85], v[154:157], v[232:235], v[82:85]
	v_mfma_f32_16x16x32_bf16 v[134:137], v[150:153], v[198:201], v[134:137]
	v_mfma_f32_16x16x32_bf16 v[130:133], v[158:161], v[198:201], v[130:133]
	v_mfma_f32_16x16x32_bf16 v[118:121], v[150:153], v[206:209], v[118:121]
	v_mfma_f32_16x16x32_bf16 v[114:117], v[158:161], v[206:209], v[114:117]
	v_mfma_f32_16x16x32_bf16 v[102:105], v[150:153], v[226:229], v[102:105]
	v_mfma_f32_16x16x32_bf16 v[98:101], v[158:161], v[226:229], v[98:101]
	v_mfma_f32_16x16x32_bf16 v[86:89], v[150:153], v[182:185], v[86:89]
	s_barrier
	v_mfma_f32_16x16x32_bf16 v[82:85], v[158:161], v[182:185], v[82:85]
	s_setprio 0
	s_mov_b32 m0, s95
	v_lshl_add_u64 v[218:219], s[92:93], 0, v[164:165]
	v_lshl_add_u64 v[250:251], s[92:93], 0, v[168:169]
	s_add_u32 s92, s92, s70
	ds_read_b128 v[182:185], v214 offset:16384
	ds_read_b128 v[194:197], v214 offset:17408
	ds_read_b128 v[198:201], v214 offset:18432
	ds_read_b128 v[202:205], v214 offset:19456
	ds_read_b128 v[206:209], v214 offset:20480
	ds_read_b128 v[210:213], v214 offset:21504
	ds_read_b128 v[226:229], v214 offset:22528
	ds_read_b128 v[232:235], v214 offset:23552
	global_load_lds_dwordx4 v[218:219], off
	s_mov_b32 m0, s31
	s_addc_u32 s93, s93, 0
	global_load_lds_dwordx4 v[250:251], off
	v_lshl_add_u64 v[236:237], s[92:93], 0, v[164:165]
	s_mov_b32 m0, s68
	v_lshl_add_u64 v[238:239], s[92:93], 0, v[168:169]
	global_load_lds_dwordx4 v[236:237], off
	s_mov_b32 m0, s69
	v_lshl_add_u64 v[240:241], s[42:43], 0, v[162:163]
	global_load_lds_dwordx4 v[238:239], off
	s_mov_b32 m0, s57
	v_lshl_add_u64 v[178:179], s[42:43], 0, v[166:167]
	global_load_lds_dwordx4 v[240:241], off
	s_mov_b32 m0, s29
	s_nop 0
	global_load_lds_dwordx4 v[178:179], off
	s_waitcnt vmcnt(8)
	s_waitcnt lgkmcnt(0)
	s_barrier
; #define PG8_STAGE(bufoff, gbase, voff) do { _Pragma("unroll") for (int _i = 0; _i < 2; ++_i) \
;         __builtin_amdgcn_global_load_lds((const unsigned*)((const char*)(gbase) + (voff)[_i]), (PG8_LAS unsigned*)(lds + (bufoff) + ldsw + _i * 8192), 16, 0, 0); } while (0)
; #define PG8_LDA(dst, b, h) do { _Pragma("unroll") for (int m = 0; m < 4; ++m) _Pragma("unroll") for (int k = 0; k < 2; ++k) dst[m][k] = *(const PG8_LAS bf16x8*)(lds + PG8_SA(b, h) + aoff + m * 2048 + k * 1024); } while (0)
; #define PG8_LDB(dst, b, h) do { _Pragma("unroll") for (int n = 0; n < 2; ++n) _Pragma("unroll") for (int k = 0; k < 2; ++k) dst[n][k] = *(const PG8_LAS bf16x8*)(lds + PG8_SB(b, h) + boff + n * 2048 + k * 1024); } while (0)
; #define PG8_MMA(ai, bj, At, Bt) do { __builtin_amdgcn_s_setprio(1); _Pragma("unroll") for (int m = 0; m < 4; ++m) _Pragma("unroll") for (int n = 0; n < 2; ++n) _Pragma("unroll") for (int k = 0; k < 2; ++k) \
;         acc[ai][bj][m][n] = __builtin_amdgcn_mfma_f32_16x16x32_bf16(Bt[n][k], At[m][k], acc[ai][bj][m][n], 0, 0, 0); __builtin_amdgcn_s_setprio(0); } while (0)
; #define PG8_WAIT_V(n) asm volatile("s_waitcnt vmcnt(" #n ")" ::: "memory")
; #define PG8_WAIT_L(n) asm volatile("s_waitcnt lgkmcnt(" #n ")" ::: "memory")
; #define PG8_BAR __builtin_amdgcn_s_barrier()
; #define PG8_SCHED __builtin_amdgcn_sched_barrier(0)
; template <class Epi, class Sched, bool ALIGN_EPI = false, bool SP2 = false>
; __device__ __forceinline__ void gemm_phase(PG8_LAS unsigned char* lds, const Gemm g, const Sched& S, const Epi& E, int tid_in) {
;     ...
;             PG8_WAIT_V(8); PG8_WAIT_L(0); PG8_BAR; PG8_MMA(1, 0, At, B0); PG8_MMA(1, 1, At, B1); PG8_BAR; PG8_SCHED;
;             PG8_LDB(B0, 1, 0); PG8_LDB(B1, 1, 1); PG8_SCHED; PG8_LDA(At, 1, 0); PG8_STAGE(PG8_SA(0, 1), a2 + hstep, voffA);
;             PG8_WAIT_V(8); PG8_WAIT_L(0); PG8_BAR; PG8_MMA(0, 0, At, B0); PG8_MMA(0, 1, At, B1); PG8_BAR; PG8_SCHED;
	s_setprio 1
	s_waitcnt lgkmcnt(0)
	v_mfma_f32_16x16x32_bf16 v[76:79], v[40:43], v[182:185], v[76:79]
	v_mfma_f32_16x16x32_bf16 v[72:75], v[52:55], v[182:185], v[72:75]
	v_mfma_f32_16x16x32_bf16 v[56:59], v[40:43], v[198:201], v[56:59]
	v_mfma_f32_16x16x32_bf16 v[48:51], v[52:55], v[198:201], v[48:51]
	v_mfma_f32_16x16x32_bf16 v[28:31], v[40:43], v[206:209], v[28:31]
	v_mfma_f32_16x16x32_bf16 v[24:27], v[52:55], v[206:209], v[24:27]
	v_mfma_f32_16x16x32_bf16 v[12:15], v[40:43], v[226:229], v[12:15]
	v_mfma_f32_16x16x32_bf16 v[8:11], v[52:55], v[226:229], v[8:11]
	v_mfma_f32_16x16x32_bf16 v[76:79], v[44:47], v[194:197], v[76:79]
	v_mfma_f32_16x16x32_bf16 v[72:75], v[60:63], v[194:197], v[72:75]
	v_mfma_f32_16x16x32_bf16 v[56:59], v[44:47], v[202:205], v[56:59]
	v_mfma_f32_16x16x32_bf16 v[48:51], v[60:63], v[202:205], v[48:51]
	v_mfma_f32_16x16x32_bf16 v[28:31], v[44:47], v[210:213], v[28:31]
	v_mfma_f32_16x16x32_bf16 v[24:27], v[60:63], v[210:213], v[24:27]
	v_mfma_f32_16x16x32_bf16 v[12:15], v[44:47], v[232:235], v[12:15]
	v_mfma_f32_16x16x32_bf16 v[8:11], v[60:63], v[232:235], v[8:11]
	v_mfma_f32_16x16x32_bf16 v[36:39], v[146:149], v[198:201], v[36:39]
	v_mfma_f32_16x16x32_bf16 v[32:35], v[154:157], v[198:201], v[32:35]
	v_mfma_f32_16x16x32_bf16 v[20:23], v[146:149], v[206:209], v[20:23]
	v_mfma_f32_16x16x32_bf16 v[16:19], v[154:157], v[206:209], v[16:19]
	v_mfma_f32_16x16x32_bf16 v[4:7], v[146:149], v[226:229], v[4:7]
	v_mfma_f32_16x16x32_bf16 v[0:3], v[154:157], v[226:229], v[0:3]
	v_mfma_f32_16x16x32_bf16 v[40:43], v[146:149], v[182:185], v[68:71]
	v_mfma_f32_16x16x32_bf16 v[44:47], v[154:157], v[182:185], v[64:67]
	v_mfma_f32_16x16x32_bf16 v[36:39], v[150:153], v[202:205], v[36:39]
	v_mfma_f32_16x16x32_bf16 v[32:35], v[158:161], v[202:205], v[32:35]
	v_mfma_f32_16x16x32_bf16 v[20:23], v[150:153], v[210:213], v[20:23]
	v_mfma_f32_16x16x32_bf16 v[16:19], v[158:161], v[210:213], v[16:19]
	v_mfma_f32_16x16x32_bf16 v[4:7], v[150:153], v[232:235], v[4:7]
	v_mfma_f32_16x16x32_bf16 v[0:3], v[158:161], v[232:235], v[0:3]
	v_mfma_f32_16x16x32_bf16 v[40:43], v[150:153], v[194:197], v[40:43]
	s_barrier
	v_mfma_f32_16x16x32_bf16 v[44:47], v[158:161], v[194:197], v[44:47]
	s_setprio 0
	v_or_b32_e32 v52, 0x18000, v215
	v_add_u32_e32 v60, 0x18400, v215
	v_add_u32_e32 v64, 0x18800, v215
	v_add_u32_e32 v68, 0x18c00, v215
	v_or_b32_e32 v146, 0x1c000, v215
	v_add_u32_e32 v150, 0x1c400, v215
	v_add_u32_e32 v154, 0x1c800, v215
	v_add_u32_e32 v158, 0x1cc00, v215
	ds_read_b128 v[52:55], v52
	ds_read_b128 v[60:63], v60
	ds_read_b128 v[64:67], v64
	ds_read_b128 v[68:71], v68
	ds_read_b128 v[146:149], v146
	ds_read_b128 v[150:153], v150
	ds_read_b128 v[154:157], v154
	ds_read_b128 v[158:161], v158
	s_add_u32 s42, s42, s70
	s_addc_u32 s43, s43, 0
	s_mov_b32 m0, s58
	v_lshl_add_u64 v[180:181], s[42:43], 0, v[162:163]
	ds_read_b128 v[182:185], v214 offset:32768
	ds_read_b128 v[194:197], v214 offset:33792
	ds_read_b128 v[198:201], v214 offset:34816
	ds_read_b128 v[202:205], v214 offset:35840
	ds_read_b128 v[206:209], v214 offset:36864
	ds_read_b128 v[210:213], v214 offset:37888
	ds_read_b128 v[226:229], v214 offset:38912
	ds_read_b128 v[232:235], v214 offset:39936
	global_load_lds_dwordx4 v[180:181], off
	v_lshl_add_u64 v[180:181], s[42:43], 0, v[166:167]
	s_mov_b32 m0, s59
	s_nop 0
	global_load_lds_dwordx4 v[180:181], off
	s_waitcnt vmcnt(8)
	s_waitcnt lgkmcnt(0)
	s_barrier
	s_setprio 1
	s_waitcnt lgkmcnt(0)
	v_mfma_f32_16x16x32_bf16 v[142:145], v[52:55], v[182:185], v[142:145]
	v_mfma_f32_16x16x32_bf16 v[138:141], v[64:67], v[182:185], v[138:141]
	v_mfma_f32_16x16x32_bf16 v[126:129], v[52:55], v[198:201], v[126:129]
	v_mfma_f32_16x16x32_bf16 v[122:125], v[64:67], v[198:201], v[122:125]
	v_mfma_f32_16x16x32_bf16 v[110:113], v[52:55], v[206:209], v[110:113]
	v_mfma_f32_16x16x32_bf16 v[106:109], v[64:67], v[206:209], v[106:109]
	v_mfma_f32_16x16x32_bf16 v[94:97], v[52:55], v[226:229], v[94:97]
	v_mfma_f32_16x16x32_bf16 v[90:93], v[64:67], v[226:229], v[90:93]
	v_mfma_f32_16x16x32_bf16 v[142:145], v[60:63], v[194:197], v[142:145]
	v_mfma_f32_16x16x32_bf16 v[138:141], v[68:71], v[194:197], v[138:141]
	v_mfma_f32_16x16x32_bf16 v[126:129], v[60:63], v[202:205], v[126:129]
	v_mfma_f32_16x16x32_bf16 v[122:125], v[68:71], v[202:205], v[122:125]
	v_mfma_f32_16x16x32_bf16 v[110:113], v[60:63], v[210:213], v[110:113]
	v_mfma_f32_16x16x32_bf16 v[106:109], v[68:71], v[210:213], v[106:109]
	v_mfma_f32_16x16x32_bf16 v[94:97], v[60:63], v[232:235], v[94:97]
	v_mfma_f32_16x16x32_bf16 v[90:93], v[68:71], v[232:235], v[90:93]
	v_mfma_f32_16x16x32_bf16 v[134:137], v[146:149], v[182:185], v[134:137]
	v_mfma_f32_16x16x32_bf16 v[130:133], v[154:157], v[182:185], v[130:133]
	v_mfma_f32_16x16x32_bf16 v[118:121], v[146:149], v[198:201], v[118:121]
	v_mfma_f32_16x16x32_bf16 v[114:117], v[154:157], v[198:201], v[114:117]
	v_mfma_f32_16x16x32_bf16 v[102:105], v[146:149], v[206:209], v[102:105]
	v_mfma_f32_16x16x32_bf16 v[98:101], v[154:157], v[206:209], v[98:101]
	v_mfma_f32_16x16x32_bf16 v[86:89], v[146:149], v[226:229], v[86:89]
	v_mfma_f32_16x16x32_bf16 v[82:85], v[154:157], v[226:229], v[82:85]
	v_mfma_f32_16x16x32_bf16 v[134:137], v[150:153], v[194:197], v[134:137]
	v_mfma_f32_16x16x32_bf16 v[130:133], v[158:161], v[194:197], v[130:133]
	v_mfma_f32_16x16x32_bf16 v[118:121], v[150:153], v[202:205], v[118:121]
	v_mfma_f32_16x16x32_bf16 v[114:117], v[158:161], v[202:205], v[114:117]
	v_mfma_f32_16x16x32_bf16 v[102:105], v[150:153], v[210:213], v[102:105]
	v_mfma_f32_16x16x32_bf16 v[98:101], v[158:161], v[210:213], v[98:101]
	v_mfma_f32_16x16x32_bf16 v[86:89], v[150:153], v[232:235], v[86:89]
	s_barrier
; #define PG8_STAGE(bufoff, gbase, voff) do { _Pragma("unroll") for (int _i = 0; _i < 2; ++_i) \
;         __builtin_amdgcn_global_load_lds((const unsigned*)((const char*)(gbase) + (voff)[_i]), (PG8_LAS unsigned*)(lds + (bufoff) + ldsw + _i * 8192), 16, 0, 0); } while (0)
; #define PG8_LDA(dst, b, h) do { _Pragma("unroll") for (int m = 0; m < 4; ++m) _Pragma("unroll") for (int k = 0; k < 2; ++k) dst[m][k] = *(const PG8_LAS bf16x8*)(lds + PG8_SA(b, h) + aoff + m * 2048 + k * 1024); } while (0)
; #define PG8_MMA(ai, bj, At, Bt) do { __builtin_amdgcn_s_setprio(1); _Pragma("unroll") for (int m = 0; m < 4; ++m) _Pragma("unroll") for (int n = 0; n < 2; ++n) _Pragma("unroll") for (int k = 0; k < 2; ++k) \
;         acc[ai][bj][m][n] = __builtin_amdgcn_mfma_f32_16x16x32_bf16(Bt[n][k], At[m][k], acc[ai][bj][m][n], 0, 0, 0); __builtin_amdgcn_s_setprio(0); } while (0)
; #define PG8_WAIT_V(n) asm volatile("s_waitcnt vmcnt(" #n ")" ::: "memory")
; #define PG8_WAIT_L(n) asm volatile("s_waitcnt lgkmcnt(" #n ")" ::: "memory")
; #define PG8_BAR __builtin_amdgcn_s_barrier()
; #define PG8_SCHED __builtin_amdgcn_sched_barrier(0)
; template <class Epi, class Sched, bool ALIGN_EPI = false, bool SP2 = false>
; __device__ __forceinline__ void gemm_phase(PG8_LAS unsigned char* lds, const Gemm g, const Sched& S, const Epi& E, int tid_in) {
;     ...
;             PG8_WAIT_V(8); PG8_WAIT_L(0); PG8_BAR; PG8_MMA(0, 0, At, B0); PG8_MMA(0, 1, At, B1); PG8_BAR; PG8_SCHED;
;             PG8_LDA(At, 1, 1); PG8_STAGE(PG8_SB(1, 0), b3, voffB); PG8_STAGE(PG8_SB(1, 1), b3 + hstep, voffB); PG8_STAGE(PG8_SA(1, 0), a3, voffA);
;             PG8_WAIT_V(8); PG8_WAIT_L(0); PG8_BAR; PG8_MMA(1, 0, At, B0); PG8_MMA(1, 1, At, B1); PG8_BAR; PG8_SCHED;
;     ...
;         if constexpr (ALIGN_EPI) { if (wr == 0) PG8_BAR; }
	v_mfma_f32_16x16x32_bf16 v[82:85], v[158:161], v[232:235], v[82:85]
	s_setprio 0
	s_mov_b32 m0, s64
	v_lshl_add_u64 v[180:181], v[218:219], 0, s[48:49]
	ds_read_b128 v[182:185], v214 offset:49152
	ds_read_b128 v[194:197], v214 offset:50176
	ds_read_b128 v[198:201], v214 offset:51200
	ds_read_b128 v[202:205], v214 offset:52224
	ds_read_b128 v[206:209], v214 offset:53248
	ds_read_b128 v[210:213], v214 offset:54272
	ds_read_b128 v[226:229], v214 offset:55296
	ds_read_b128 v[232:235], v214 offset:56320
	global_load_lds_dwordx4 v[180:181], off
	v_lshl_add_u64 v[180:181], v[250:251], 0, s[48:49]
	s_mov_b32 m0, s65
	v_lshl_add_u64 v[178:179], v[178:179], 0, s[48:49]
	global_load_lds_dwordx4 v[180:181], off
	v_lshl_add_u64 v[180:181], v[236:237], 0, s[48:49]
	s_mov_b32 m0, s61
	s_nop 0
	global_load_lds_dwordx4 v[180:181], off
	v_lshl_add_u64 v[180:181], v[238:239], 0, s[48:49]
	s_mov_b32 m0, s62
	s_nop 0
	global_load_lds_dwordx4 v[180:181], off
	v_lshl_add_u64 v[180:181], v[240:241], 0, s[48:49]
	s_mov_b32 m0, s72
	s_nop 0
	global_load_lds_dwordx4 v[180:181], off
	s_mov_b32 m0, s73
	s_nop 0
	global_load_lds_dwordx4 v[178:179], off
	s_waitcnt vmcnt(8)
	s_waitcnt lgkmcnt(0)
	s_barrier
	s_setprio 1
	s_waitcnt lgkmcnt(0)
	v_mfma_f32_16x16x32_bf16 v[76:79], v[52:55], v[182:185], v[76:79]
	v_mfma_f32_16x16x32_bf16 v[72:75], v[64:67], v[182:185], v[72:75]
	v_mfma_f32_16x16x32_bf16 v[56:59], v[52:55], v[198:201], v[56:59]
	v_mfma_f32_16x16x32_bf16 v[48:51], v[64:67], v[198:201], v[48:51]
	v_mfma_f32_16x16x32_bf16 v[28:31], v[52:55], v[206:209], v[28:31]
	v_mfma_f32_16x16x32_bf16 v[24:27], v[64:67], v[206:209], v[24:27]
	v_mfma_f32_16x16x32_bf16 v[12:15], v[52:55], v[226:229], v[12:15]
	v_mfma_f32_16x16x32_bf16 v[8:11], v[64:67], v[226:229], v[8:11]
	v_mfma_f32_16x16x32_bf16 v[76:79], v[60:63], v[194:197], v[76:79]
	v_mfma_f32_16x16x32_bf16 v[72:75], v[68:71], v[194:197], v[72:75]
	v_mfma_f32_16x16x32_bf16 v[56:59], v[60:63], v[202:205], v[56:59]
	v_mfma_f32_16x16x32_bf16 v[48:51], v[68:71], v[202:205], v[48:51]
	v_mfma_f32_16x16x32_bf16 v[28:31], v[60:63], v[210:213], v[28:31]
	v_mfma_f32_16x16x32_bf16 v[24:27], v[68:71], v[210:213], v[24:27]
	v_mfma_f32_16x16x32_bf16 v[12:15], v[60:63], v[232:235], v[12:15]
	v_mfma_f32_16x16x32_bf16 v[8:11], v[68:71], v[232:235], v[8:11]
	v_mfma_f32_16x16x32_bf16 v[40:43], v[146:149], v[182:185], v[40:43]
	v_mfma_f32_16x16x32_bf16 v[68:71], v[150:153], v[194:197], v[40:43]
	v_mfma_f32_16x16x32_bf16 v[40:43], v[154:157], v[182:185], v[44:47]
	v_mfma_f32_16x16x32_bf16 v[36:39], v[146:149], v[198:201], v[36:39]
	v_mfma_f32_16x16x32_bf16 v[32:35], v[154:157], v[198:201], v[32:35]
	v_mfma_f32_16x16x32_bf16 v[20:23], v[146:149], v[206:209], v[20:23]
	v_mfma_f32_16x16x32_bf16 v[16:19], v[154:157], v[206:209], v[16:19]
	v_mfma_f32_16x16x32_bf16 v[4:7], v[146:149], v[226:229], v[4:7]
	v_mfma_f32_16x16x32_bf16 v[0:3], v[154:157], v[226:229], v[0:3]
	v_mfma_f32_16x16x32_bf16 v[64:67], v[158:161], v[194:197], v[40:43]
	v_mfma_f32_16x16x32_bf16 v[36:39], v[150:153], v[202:205], v[36:39]
	v_mfma_f32_16x16x32_bf16 v[32:35], v[158:161], v[202:205], v[32:35]
	v_mfma_f32_16x16x32_bf16 v[20:23], v[150:153], v[210:213], v[20:23]
	v_mfma_f32_16x16x32_bf16 v[16:19], v[158:161], v[210:213], v[16:19]
	v_mfma_f32_16x16x32_bf16 v[4:7], v[150:153], v[232:235], v[4:7]
	s_barrier
	v_mfma_f32_16x16x32_bf16 v[0:3], v[158:161], v[232:235], v[0:3]
	s_setprio 0
	s_add_u32 s40, s40, 0x100
	s_addc_u32 s41, s41, 0
	s_add_u32 s26, s26, 0x100
	s_addc_u32 s27, s27, 0
	s_cmp_ge_u32 s44, s66
	s_mov_b32 s42, s44
	s_cbranch_scc0 .LBB0_508
	s_and_b64 vcc, exec, s[78:79]
	s_cbranch_vccz .LBB0_511
	s_barrier

; #define PG8_STAGE(bufoff, gbase, voff) do { _Pragma("unroll") for (int _i = 0; _i < 2; ++_i) \
;         __builtin_amdgcn_global_load_lds((const unsigned*)((const char*)(gbase) + (voff)[_i]), (PG8_LAS unsigned*)(lds + (bufoff) + ldsw + _i * 8192), 16, 0, 0); } while (0)
; #define PG8_LDA(dst, b, h) do { _Pragma("unroll") for (int m = 0; m < 4; ++m) _Pragma("unroll") for (int k = 0; k < 2; ++k) dst[m][k] = *(const PG8_LAS bf16x8*)(lds + PG8_SA(b, h) + aoff + m * 2048 + k * 1024); } while (0)
; #define PG8_LDB(dst, b, h) do { _Pragma("unroll") for (int n = 0; n < 2; ++n) _Pragma("unroll") for (int k = 0; k < 2; ++k) dst[n][k] = *(const PG8_LAS bf16x8*)(lds + PG8_SB(b, h) + boff + n * 2048 + k * 1024); } while (0)
; #define PG8_MMA(ai, bj, At, Bt) do { __builtin_amdgcn_s_setprio(1); _Pragma("unroll") for (int m = 0; m < 4; ++m) _Pragma("unroll") for (int n = 0; n < 2; ++n) _Pragma("unroll") for (int k = 0; k < 2; ++k) \
;         acc[ai][bj][m][n] = __builtin_amdgcn_mfma_f32_16x16x32_bf16(Bt[n][k], At[m][k], acc[ai][bj][m][n], 0, 0, 0); __builtin_amdgcn_s_setprio(0); } while (0)
; #define PG8_WAIT_V(n) asm volatile("s_waitcnt vmcnt(" #n ")" ::: "memory")
; #define PG8_WAIT_L(n) asm volatile("s_waitcnt lgkmcnt(" #n ")" ::: "memory")
; #define PG8_BAR __builtin_amdgcn_s_barrier()
; #define PG8_SCHED __builtin_amdgcn_sched_barrier(0)
; template <class Epi, class Sched, bool ALIGN_EPI = false, bool SP2 = false>
; __device__ __forceinline__ void gemm_phase(PG8_LAS unsigned char* lds, const Gemm g, const Sched& S, const Epi& E, int tid_in) {
;     ...
;             PG8_LDB(B0, 0, 0); PG8_LDB(B1, 0, 1); PG8_SCHED; PG8_LDA(At, 0, 0); PG8_STAGE(PG8_SA(1, 1), a1 + hstep, voffA);
;             PG8_WAIT_V(8); PG8_WAIT_L(0); PG8_BAR; PG8_MMA(0, 0, At, B0); PG8_MMA(0, 1, At, B1); PG8_BAR; PG8_SCHED;
;             PG8_LDA(At, 0, 1); PG8_STAGE(PG8_SB(0, 0), b2, voffB); PG8_STAGE(PG8_SB(0, 1), b2 + hstep, voffB); PG8_STAGE(PG8_SA(0, 0), a2, voffA);
;             PG8_WAIT_V(8); PG8_WAIT_L(0); PG8_BAR; PG8_MMA(1, 0, At, B0); PG8_MMA(1, 1, At, B1); PG8_BAR; PG8_SCHED;
.LBB0_780:
	v_or_b32_e32 v142, 0x10000, v145
	v_add_u32_e32 v143, 0x10400, v145
	ds_read_b128 v[148:151], v142
	ds_read_b128 v[152:155], v143
	v_add_u32_e32 v142, 0x10800, v145
	v_add_u32_e32 v143, 0x10c00, v145
	ds_read_b128 v[156:159], v142
	ds_read_b128 v[160:163], v143
	v_or_b32_e32 v142, 0x14000, v145
	v_add_u32_e32 v143, 0x14400, v145
	ds_read_b128 v[164:167], v142
	ds_read_b128 v[168:171], v143
	v_add_u32_e32 v142, 0x14800, v145
	v_add_u32_e32 v143, 0x14c00, v145
	ds_read_b128 v[172:175], v142
	ds_read_b128 v[194:197], v143
	s_add_u32 s70, s68, 0xfffc0080
	s_addc_u32 s71, s69, -1
	s_cmp_eq_u32 s82, 12
	s_cselect_b32 s73, s45, s71
	s_cselect_b32 s72, s78, s70
	s_cselect_b32 s71, s43, s81
	s_cselect_b32 s70, s79, s80
	v_lshl_add_u64 v[142:143], s[68:69], 0, v[138:139]
	s_add_i32 m0, s22, 0xc000
	ds_read_b128 v[198:201], v144
	ds_read_b128 v[202:205], v144 offset:1024
	ds_read_b128 v[206:209], v144 offset:2048
	ds_read_b128 v[210:213], v144 offset:3072
	ds_read_b128 v[214:217], v144 offset:4096
	ds_read_b128 v[248:251], v144 offset:5120
	ds_read_b128 v[232:235], v144 offset:6144
	ds_read_b128 v[226:229], v144 offset:7168
	global_load_lds_dwordx4 v[142:143], off
	v_lshl_add_u64 v[142:143], s[68:69], 0, v[140:141]
	s_add_i32 m0, s22, 0xe000
	s_nop 0
	global_load_lds_dwordx4 v[142:143], off
	s_waitcnt vmcnt(8)
	s_waitcnt lgkmcnt(0)
	s_barrier
	s_setprio 1
	s_waitcnt lgkmcnt(0)
	v_mfma_f32_16x16x32_bf16 v[126:129], v[148:151], v[198:201], v[126:129]
	v_mfma_f32_16x16x32_bf16 v[118:121], v[156:159], v[198:201], v[118:121]
	v_mfma_f32_16x16x32_bf16 v[110:113], v[148:151], v[206:209], v[110:113]
	v_mfma_f32_16x16x32_bf16 v[102:105], v[156:159], v[206:209], v[102:105]
	v_mfma_f32_16x16x32_bf16 v[94:97], v[148:151], v[214:217], v[94:97]
	v_mfma_f32_16x16x32_bf16 v[86:89], v[156:159], v[214:217], v[86:89]
	v_mfma_f32_16x16x32_bf16 v[76:79], v[148:151], v[232:235], v[76:79]
	v_mfma_f32_16x16x32_bf16 v[68:71], v[156:159], v[232:235], v[68:71]
	v_mfma_f32_16x16x32_bf16 v[126:129], v[152:155], v[202:205], v[126:129]
	v_mfma_f32_16x16x32_bf16 v[118:121], v[160:163], v[202:205], v[118:121]
	v_mfma_f32_16x16x32_bf16 v[110:113], v[152:155], v[210:213], v[110:113]
	v_mfma_f32_16x16x32_bf16 v[102:105], v[160:163], v[210:213], v[102:105]
	v_mfma_f32_16x16x32_bf16 v[94:97], v[152:155], v[248:251], v[94:97]
	v_mfma_f32_16x16x32_bf16 v[86:89], v[160:163], v[248:251], v[86:89]
	v_mfma_f32_16x16x32_bf16 v[76:79], v[152:155], v[226:229], v[76:79]
	v_mfma_f32_16x16x32_bf16 v[68:71], v[160:163], v[226:229], v[68:71]
	v_mfma_f32_16x16x32_bf16 v[122:125], v[164:167], v[198:201], v[122:125]
	v_mfma_f32_16x16x32_bf16 v[114:117], v[172:175], v[198:201], v[114:117]
	v_mfma_f32_16x16x32_bf16 v[106:109], v[164:167], v[206:209], v[106:109]
	v_mfma_f32_16x16x32_bf16 v[98:101], v[172:175], v[206:209], v[98:101]
	v_mfma_f32_16x16x32_bf16 v[90:93], v[164:167], v[214:217], v[90:93]
	v_mfma_f32_16x16x32_bf16 v[82:85], v[172:175], v[214:217], v[82:85]
	v_mfma_f32_16x16x32_bf16 v[72:75], v[164:167], v[232:235], v[72:75]
	v_mfma_f32_16x16x32_bf16 v[64:67], v[172:175], v[232:235], v[64:67]
	v_mfma_f32_16x16x32_bf16 v[122:125], v[168:171], v[202:205], v[122:125]
	v_mfma_f32_16x16x32_bf16 v[114:117], v[194:197], v[202:205], v[114:117]
	v_mfma_f32_16x16x32_bf16 v[106:109], v[168:171], v[210:213], v[106:109]
	v_mfma_f32_16x16x32_bf16 v[98:101], v[194:197], v[210:213], v[98:101]
	v_mfma_f32_16x16x32_bf16 v[90:93], v[168:171], v[248:251], v[90:93]
	v_mfma_f32_16x16x32_bf16 v[82:85], v[194:197], v[248:251], v[82:85]
	v_mfma_f32_16x16x32_bf16 v[72:75], v[168:171], v[226:229], v[72:75]
	s_barrier
	v_mfma_f32_16x16x32_bf16 v[64:67], v[194:197], v[226:229], v[64:67]
	s_setprio 0
	s_mov_b32 m0, s24
	v_lshl_add_u64 v[142:143], s[70:71], 0, v[134:135]
	s_add_u32 s84, s70, 0x40000
	ds_read_b128 v[198:201], v144 offset:16384
	ds_read_b128 v[202:205], v144 offset:17408
	ds_read_b128 v[206:209], v144 offset:18432
	ds_read_b128 v[210:213], v144 offset:19456
	ds_read_b128 v[214:217], v144 offset:20480
	ds_read_b128 v[226:229], v144 offset:21504
	ds_read_b128 v[232:235], v144 offset:22528
	ds_read_b128 v[248:251], v144 offset:23552
	global_load_lds_dwordx4 v[142:143], off
	v_lshl_add_u64 v[176:177], s[70:71], 0, v[130:131]
	s_mov_b32 m0, s25
	s_addc_u32 s85, s71, 0
	global_load_lds_dwordx4 v[176:177], off
	v_lshl_add_u64 v[182:183], s[84:85], 0, v[134:135]
	s_mov_b32 m0, s26
	v_lshl_add_u64 v[184:185], s[72:73], 0, v[132:133]
	global_load_lds_dwordx4 v[182:183], off
	v_lshl_add_u64 v[182:183], s[84:85], 0, v[130:131]
	s_mov_b32 m0, s27
	s_nop 0
	global_load_lds_dwordx4 v[182:183], off
	v_lshl_add_u64 v[182:183], s[72:73], 0, v[136:137]
	s_mov_b32 m0, s22
	s_nop 0
	global_load_lds_dwordx4 v[182:183], off
	s_mov_b32 m0, s29
	s_nop 0
	global_load_lds_dwordx4 v[184:185], off
	s_waitcnt vmcnt(8)
	s_waitcnt lgkmcnt(0)
	s_barrier
; #define PG8_STAGE(bufoff, gbase, voff) do { _Pragma("unroll") for (int _i = 0; _i < 2; ++_i) \
;         __builtin_amdgcn_global_load_lds((const unsigned*)((const char*)(gbase) + (voff)[_i]), (PG8_LAS unsigned*)(lds + (bufoff) + ldsw + _i * 8192), 16, 0, 0); } while (0)
; #define PG8_LDA(dst, b, h) do { _Pragma("unroll") for (int m = 0; m < 4; ++m) _Pragma("unroll") for (int k = 0; k < 2; ++k) dst[m][k] = *(const PG8_LAS bf16x8*)(lds + PG8_SA(b, h) + aoff + m * 2048 + k * 1024); } while (0)
; #define PG8_LDB(dst, b, h) do { _Pragma("unroll") for (int n = 0; n < 2; ++n) _Pragma("unroll") for (int k = 0; k < 2; ++k) dst[n][k] = *(const PG8_LAS bf16x8*)(lds + PG8_SB(b, h) + boff + n * 2048 + k * 1024); } while (0)
; #define PG8_MMA(ai, bj, At, Bt) do { __builtin_amdgcn_s_setprio(1); _Pragma("unroll") for (int m = 0; m < 4; ++m) _Pragma("unroll") for (int n = 0; n < 2; ++n) _Pragma("unroll") for (int k = 0; k < 2; ++k) \
;         acc[ai][bj][m][n] = __builtin_amdgcn_mfma_f32_16x16x32_bf16(Bt[n][k], At[m][k], acc[ai][bj][m][n], 0, 0, 0); __builtin_amdgcn_s_setprio(0); } while (0)
; #define PG8_WAIT_V(n) asm volatile("s_waitcnt vmcnt(" #n ")" ::: "memory")
; #define PG8_WAIT_L(n) asm volatile("s_waitcnt lgkmcnt(" #n ")" ::: "memory")
; #define PG8_BAR __builtin_amdgcn_s_barrier()
; #define PG8_SCHED __builtin_amdgcn_sched_barrier(0)
; template <class Epi, class Sched, bool ALIGN_EPI = false, bool SP2 = false>
; __device__ __forceinline__ void gemm_phase(PG8_LAS unsigned char* lds, const Gemm g, const Sched& S, const Epi& E, int tid_in) {
;     ...
;             PG8_WAIT_V(8); PG8_WAIT_L(0); PG8_BAR; PG8_MMA(1, 0, At, B0); PG8_MMA(1, 1, At, B1); PG8_BAR; PG8_SCHED;
;             PG8_LDB(B0, 1, 0); PG8_LDB(B1, 1, 1); PG8_SCHED; PG8_LDA(At, 1, 0); PG8_STAGE(PG8_SA(0, 1), a2 + hstep, voffA);
;             PG8_WAIT_V(8); PG8_WAIT_L(0); PG8_BAR; PG8_MMA(0, 0, At, B0); PG8_MMA(0, 1, At, B1); PG8_BAR; PG8_SCHED;
	s_setprio 1
	s_waitcnt lgkmcnt(0)
	v_mfma_f32_16x16x32_bf16 v[60:63], v[148:151], v[198:201], v[60:63]
	v_mfma_f32_16x16x32_bf16 v[52:55], v[156:159], v[198:201], v[52:55]
	v_mfma_f32_16x16x32_bf16 v[44:47], v[148:151], v[206:209], v[44:47]
	v_mfma_f32_16x16x32_bf16 v[36:39], v[156:159], v[206:209], v[36:39]
	v_mfma_f32_16x16x32_bf16 v[28:31], v[148:151], v[214:217], v[28:31]
	v_mfma_f32_16x16x32_bf16 v[20:23], v[156:159], v[214:217], v[20:23]
	v_mfma_f32_16x16x32_bf16 v[12:15], v[148:151], v[232:235], v[12:15]
	v_mfma_f32_16x16x32_bf16 v[4:7], v[156:159], v[232:235], v[4:7]
	v_mfma_f32_16x16x32_bf16 v[60:63], v[152:155], v[202:205], v[60:63]
	v_mfma_f32_16x16x32_bf16 v[52:55], v[160:163], v[202:205], v[52:55]
	v_mfma_f32_16x16x32_bf16 v[44:47], v[152:155], v[210:213], v[44:47]
	v_mfma_f32_16x16x32_bf16 v[36:39], v[160:163], v[210:213], v[36:39]
	v_mfma_f32_16x16x32_bf16 v[28:31], v[152:155], v[226:229], v[28:31]
	v_mfma_f32_16x16x32_bf16 v[20:23], v[160:163], v[226:229], v[20:23]
	v_mfma_f32_16x16x32_bf16 v[12:15], v[152:155], v[248:251], v[12:15]
	v_mfma_f32_16x16x32_bf16 v[4:7], v[160:163], v[248:251], v[4:7]
	v_mfma_f32_16x16x32_bf16 v[56:59], v[164:167], v[198:201], v[56:59]
	v_mfma_f32_16x16x32_bf16 v[48:51], v[172:175], v[198:201], v[48:51]
	v_mfma_f32_16x16x32_bf16 v[40:43], v[164:167], v[206:209], v[40:43]
	v_mfma_f32_16x16x32_bf16 v[32:35], v[172:175], v[206:209], v[32:35]
	v_mfma_f32_16x16x32_bf16 v[24:27], v[164:167], v[214:217], v[24:27]
	v_mfma_f32_16x16x32_bf16 v[16:19], v[172:175], v[214:217], v[16:19]
	v_mfma_f32_16x16x32_bf16 v[8:11], v[164:167], v[232:235], v[8:11]
	v_mfma_f32_16x16x32_bf16 v[0:3], v[172:175], v[232:235], v[0:3]
	v_mfma_f32_16x16x32_bf16 v[56:59], v[168:171], v[202:205], v[56:59]
	v_mfma_f32_16x16x32_bf16 v[48:51], v[194:197], v[202:205], v[48:51]
	v_mfma_f32_16x16x32_bf16 v[40:43], v[168:171], v[210:213], v[40:43]
	v_mfma_f32_16x16x32_bf16 v[32:35], v[194:197], v[210:213], v[32:35]
	v_mfma_f32_16x16x32_bf16 v[24:27], v[168:171], v[226:229], v[24:27]
	v_mfma_f32_16x16x32_bf16 v[16:19], v[194:197], v[226:229], v[16:19]
	v_mfma_f32_16x16x32_bf16 v[8:11], v[168:171], v[248:251], v[8:11]
	s_barrier
	v_mfma_f32_16x16x32_bf16 v[0:3], v[194:197], v[248:251], v[0:3]
	s_setprio 0
	v_or_b32_e32 v148, 0x18000, v145
	v_add_u32_e32 v152, 0x18400, v145
	v_add_u32_e32 v156, 0x18800, v145
	v_add_u32_e32 v160, 0x18c00, v145
	v_or_b32_e32 v164, 0x1c000, v145
	v_add_u32_e32 v168, 0x1c400, v145
	v_add_u32_e32 v172, 0x1c800, v145
	ds_read_b128 v[148:151], v148
	ds_read_b128 v[152:155], v152
	ds_read_b128 v[156:159], v156
	ds_read_b128 v[160:163], v160
	ds_read_b128 v[164:167], v164
	ds_read_b128 v[168:171], v168
	v_add_u32_e32 v178, 0x1cc00, v145
	ds_read_b128 v[172:175], v172
	ds_read_b128 v[194:197], v178
	s_add_u32 s72, s72, 0x40000
	s_addc_u32 s73, s73, 0
	s_mov_b32 m0, s31
	v_lshl_add_u64 v[218:219], s[72:73], 0, v[136:137]
	ds_read_b128 v[198:201], v144 offset:32768
	ds_read_b128 v[202:205], v144 offset:33792
	ds_read_b128 v[206:209], v144 offset:34816
	ds_read_b128 v[210:213], v144 offset:35840
	ds_read_b128 v[214:217], v144 offset:36864
	ds_read_b128 v[226:229], v144 offset:37888
	ds_read_b128 v[232:235], v144 offset:38912
	ds_read_b128 v[248:251], v144 offset:39936
	global_load_lds_dwordx4 v[218:219], off
	v_lshl_add_u64 v[218:219], s[72:73], 0, v[132:133]
	s_mov_b32 m0, s57
	s_nop 0
	global_load_lds_dwordx4 v[218:219], off
	s_waitcnt vmcnt(8)
	s_waitcnt lgkmcnt(0)
	s_barrier
	s_setprio 1
	s_waitcnt lgkmcnt(0)
	v_mfma_f32_16x16x32_bf16 v[126:129], v[148:151], v[198:201], v[126:129]
	v_mfma_f32_16x16x32_bf16 v[118:121], v[156:159], v[198:201], v[118:121]
	v_mfma_f32_16x16x32_bf16 v[110:113], v[148:151], v[206:209], v[110:113]
	v_mfma_f32_16x16x32_bf16 v[102:105], v[156:159], v[206:209], v[102:105]
	v_mfma_f32_16x16x32_bf16 v[94:97], v[148:151], v[214:217], v[94:97]
	v_mfma_f32_16x16x32_bf16 v[86:89], v[156:159], v[214:217], v[86:89]
	v_mfma_f32_16x16x32_bf16 v[76:79], v[148:151], v[232:235], v[76:79]
	v_mfma_f32_16x16x32_bf16 v[68:71], v[156:159], v[232:235], v[68:71]
	v_mfma_f32_16x16x32_bf16 v[126:129], v[152:155], v[202:205], v[126:129]
	v_mfma_f32_16x16x32_bf16 v[118:121], v[160:163], v[202:205], v[118:121]
	v_mfma_f32_16x16x32_bf16 v[110:113], v[152:155], v[210:213], v[110:113]
	v_mfma_f32_16x16x32_bf16 v[102:105], v[160:163], v[210:213], v[102:105]
	v_mfma_f32_16x16x32_bf16 v[94:97], v[152:155], v[226:229], v[94:97]
	v_mfma_f32_16x16x32_bf16 v[86:89], v[160:163], v[226:229], v[86:89]
	v_mfma_f32_16x16x32_bf16 v[76:79], v[152:155], v[248:251], v[76:79]
	v_mfma_f32_16x16x32_bf16 v[68:71], v[160:163], v[248:251], v[68:71]
	v_mfma_f32_16x16x32_bf16 v[122:125], v[164:167], v[198:201], v[122:125]
	v_mfma_f32_16x16x32_bf16 v[114:117], v[172:175], v[198:201], v[114:117]
	v_mfma_f32_16x16x32_bf16 v[106:109], v[164:167], v[206:209], v[106:109]
	v_mfma_f32_16x16x32_bf16 v[98:101], v[172:175], v[206:209], v[98:101]
	v_mfma_f32_16x16x32_bf16 v[90:93], v[164:167], v[214:217], v[90:93]
	v_mfma_f32_16x16x32_bf16 v[82:85], v[172:175], v[214:217], v[82:85]
	v_mfma_f32_16x16x32_bf16 v[72:75], v[164:167], v[232:235], v[72:75]
	v_mfma_f32_16x16x32_bf16 v[64:67], v[172:175], v[232:235], v[64:67]
	v_mfma_f32_16x16x32_bf16 v[122:125], v[168:171], v[202:205], v[122:125]
	v_mfma_f32_16x16x32_bf16 v[114:117], v[194:197], v[202:205], v[114:117]
	v_mfma_f32_16x16x32_bf16 v[106:109], v[168:171], v[210:213], v[106:109]
	v_mfma_f32_16x16x32_bf16 v[98:101], v[194:197], v[210:213], v[98:101]
	v_mfma_f32_16x16x32_bf16 v[90:93], v[168:171], v[226:229], v[90:93]
	v_mfma_f32_16x16x32_bf16 v[82:85], v[194:197], v[226:229], v[82:85]
	v_mfma_f32_16x16x32_bf16 v[72:75], v[168:171], v[248:251], v[72:75]
	s_barrier
; #define PG8_STAGE(bufoff, gbase, voff) do { _Pragma("unroll") for (int _i = 0; _i < 2; ++_i) \
;         __builtin_amdgcn_global_load_lds((const unsigned*)((const char*)(gbase) + (voff)[_i]), (PG8_LAS unsigned*)(lds + (bufoff) + ldsw + _i * 8192), 16, 0, 0); } while (0)
; #define PG8_LDA(dst, b, h) do { _Pragma("unroll") for (int m = 0; m < 4; ++m) _Pragma("unroll") for (int k = 0; k < 2; ++k) dst[m][k] = *(const PG8_LAS bf16x8*)(lds + PG8_SA(b, h) + aoff + m * 2048 + k * 1024); } while (0)
; #define PG8_MMA(ai, bj, At, Bt) do { __builtin_amdgcn_s_setprio(1); _Pragma("unroll") for (int m = 0; m < 4; ++m) _Pragma("unroll") for (int n = 0; n < 2; ++n) _Pragma("unroll") for (int k = 0; k < 2; ++k) \
;         acc[ai][bj][m][n] = __builtin_amdgcn_mfma_f32_16x16x32_bf16(Bt[n][k], At[m][k], acc[ai][bj][m][n], 0, 0, 0); __builtin_amdgcn_s_setprio(0); } while (0)
; #define PG8_WAIT_V(n) asm volatile("s_waitcnt vmcnt(" #n ")" ::: "memory")
; #define PG8_WAIT_L(n) asm volatile("s_waitcnt lgkmcnt(" #n ")" ::: "memory")
; #define PG8_BAR __builtin_amdgcn_s_barrier()
; #define PG8_SCHED __builtin_amdgcn_sched_barrier(0)
; template <class Epi, class Sched, bool ALIGN_EPI = false, bool SP2 = false>
; __device__ __forceinline__ void gemm_phase(PG8_LAS unsigned char* lds, const Gemm g, const Sched& S, const Epi& E, int tid_in) {
;     ...
;             PG8_WAIT_V(8); PG8_WAIT_L(0); PG8_BAR; PG8_MMA(0, 0, At, B0); PG8_MMA(0, 1, At, B1); PG8_BAR; PG8_SCHED;
;             PG8_LDA(At, 1, 1); PG8_STAGE(PG8_SB(1, 0), b3, voffB); PG8_STAGE(PG8_SB(1, 1), b3 + hstep, voffB); PG8_STAGE(PG8_SA(1, 0), a3, voffA);
;             PG8_WAIT_V(8); PG8_WAIT_L(0); PG8_BAR; PG8_MMA(1, 0, At, B0); PG8_MMA(1, 1, At, B1); PG8_BAR; PG8_SCHED;
;     ...
;         if constexpr (ALIGN_EPI) { if (wr == 0) PG8_BAR; }
	v_mfma_f32_16x16x32_bf16 v[64:67], v[194:197], v[248:251], v[64:67]
	s_setprio 0
	s_mov_b32 m0, s58
	v_lshl_add_u64 v[142:143], v[142:143], 0, s[48:49]
	s_add_u32 s70, s70, 0x40080
	ds_read_b128 v[198:201], v144 offset:49152
	ds_read_b128 v[202:205], v144 offset:50176
	ds_read_b128 v[206:209], v144 offset:51200
	ds_read_b128 v[210:213], v144 offset:52224
	ds_read_b128 v[214:217], v144 offset:53248
	ds_read_b128 v[226:229], v144 offset:54272
	ds_read_b128 v[232:235], v144 offset:55296
	ds_read_b128 v[248:251], v144 offset:56320
	global_load_lds_dwordx4 v[142:143], off
	v_lshl_add_u64 v[142:143], v[176:177], 0, s[48:49]
	s_mov_b32 m0, s59
	s_addc_u32 s71, s71, 0
	global_load_lds_dwordx4 v[142:143], off
	v_lshl_add_u64 v[142:143], s[70:71], 0, v[134:135]
	s_mov_b32 m0, s63
	s_nop 0
	global_load_lds_dwordx4 v[142:143], off
	v_lshl_add_u64 v[142:143], s[70:71], 0, v[130:131]
	s_mov_b32 m0, s67
	s_nop 0
	global_load_lds_dwordx4 v[142:143], off
	v_lshl_add_u64 v[142:143], v[182:183], 0, s[48:49]
	s_mov_b32 m0, s61
	s_nop 0
	global_load_lds_dwordx4 v[142:143], off
	v_lshl_add_u64 v[142:143], v[184:185], 0, s[48:49]
	s_mov_b32 m0, s62
	s_nop 0
	global_load_lds_dwordx4 v[142:143], off
	s_waitcnt vmcnt(8)
	s_waitcnt lgkmcnt(0)
	s_barrier
	s_setprio 1
	s_waitcnt lgkmcnt(0)
	v_mfma_f32_16x16x32_bf16 v[60:63], v[148:151], v[198:201], v[60:63]
	v_mfma_f32_16x16x32_bf16 v[52:55], v[156:159], v[198:201], v[52:55]
	v_mfma_f32_16x16x32_bf16 v[44:47], v[148:151], v[206:209], v[44:47]
	v_mfma_f32_16x16x32_bf16 v[36:39], v[156:159], v[206:209], v[36:39]
	v_mfma_f32_16x16x32_bf16 v[28:31], v[148:151], v[214:217], v[28:31]
	v_mfma_f32_16x16x32_bf16 v[20:23], v[156:159], v[214:217], v[20:23]
	v_mfma_f32_16x16x32_bf16 v[12:15], v[148:151], v[232:235], v[12:15]
	v_mfma_f32_16x16x32_bf16 v[4:7], v[156:159], v[232:235], v[4:7]
	v_mfma_f32_16x16x32_bf16 v[60:63], v[152:155], v[202:205], v[60:63]
	v_mfma_f32_16x16x32_bf16 v[52:55], v[160:163], v[202:205], v[52:55]
	v_mfma_f32_16x16x32_bf16 v[44:47], v[152:155], v[210:213], v[44:47]
	v_mfma_f32_16x16x32_bf16 v[36:39], v[160:163], v[210:213], v[36:39]
	v_mfma_f32_16x16x32_bf16 v[28:31], v[152:155], v[226:229], v[28:31]
	v_mfma_f32_16x16x32_bf16 v[20:23], v[160:163], v[226:229], v[20:23]
	v_mfma_f32_16x16x32_bf16 v[12:15], v[152:155], v[248:251], v[12:15]
	v_mfma_f32_16x16x32_bf16 v[4:7], v[160:163], v[248:251], v[4:7]
	v_mfma_f32_16x16x32_bf16 v[56:59], v[164:167], v[198:201], v[56:59]
	v_mfma_f32_16x16x32_bf16 v[48:51], v[172:175], v[198:201], v[48:51]
	v_mfma_f32_16x16x32_bf16 v[40:43], v[164:167], v[206:209], v[40:43]
	v_mfma_f32_16x16x32_bf16 v[32:35], v[172:175], v[206:209], v[32:35]
	v_mfma_f32_16x16x32_bf16 v[24:27], v[164:167], v[214:217], v[24:27]
	v_mfma_f32_16x16x32_bf16 v[16:19], v[172:175], v[214:217], v[16:19]
	v_mfma_f32_16x16x32_bf16 v[8:11], v[164:167], v[232:235], v[8:11]
	v_mfma_f32_16x16x32_bf16 v[0:3], v[172:175], v[232:235], v[0:3]
	v_mfma_f32_16x16x32_bf16 v[56:59], v[168:171], v[202:205], v[56:59]
	v_mfma_f32_16x16x32_bf16 v[48:51], v[194:197], v[202:205], v[48:51]
	v_mfma_f32_16x16x32_bf16 v[40:43], v[168:171], v[210:213], v[40:43]
	v_mfma_f32_16x16x32_bf16 v[32:35], v[194:197], v[210:213], v[32:35]
	v_mfma_f32_16x16x32_bf16 v[24:27], v[168:171], v[226:229], v[24:27]
	v_mfma_f32_16x16x32_bf16 v[16:19], v[194:197], v[226:229], v[16:19]
	v_mfma_f32_16x16x32_bf16 v[8:11], v[168:171], v[248:251], v[8:11]
	s_barrier
	v_mfma_f32_16x16x32_bf16 v[0:3], v[194:197], v[248:251], v[0:3]
	s_setprio 0
	s_add_i32 s82, s82, 2
	s_add_u32 s68, s68, 0x100
	s_addc_u32 s69, s69, 0
	s_add_u32 s80, s80, 0x100
	s_addc_u32 s81, s81, 0
	s_cmp_gt_u32 s82, 13
	s_cbranch_scc0 .LBB0_780
	s_and_b64 vcc, exec, s[40:41]
	s_cbranch_vccz .LBB0_783
	s_barrier
